# NSA top-16 selection rewritten: lane=query, integer compare+addc ranking per wave octet, causal octet skip; branch island
# speedup vs baseline: 1.0412x; 1.0225x over previous
; DI void task_nsa(const P& p, int layer, int task, bf16_t* sm, int dm) {
;     ...
;   __syncthreads();
;   for (int qi = 0; qi < 8; ++qi) {
;     const int qq = wv * 8 + qi, qpos = q0 + qq, j = lane, cur = qpos >> 6;
;     const float imp = cbuf[j * 65 + qq];
;     const bool valid = j <= cur;
;     const bool forced = (j == 0) || (j == cur) || (j == cur - 1);
;     const float score = valid ? imp + (forced ? 1e4f : 0.f) : -1e30f;
;     int rank = 0;
; #pragma unroll 4
;     for (int jp = 0; jp < 64; ++jp) {
;       const float sj = __int_as_float(__builtin_amdgcn_readlane(__float_as_int(score), jp));
;       rank += ((sj > score) || (sj == score && jp < j)) ? 1 : 0;
;     }
;     const unsigned long long mk = __ballot(rank < 16);
;     if (lane == 0) masks[qq] = mk;
;   }
.LBB0_684:
	v_mul_u32_u24_e32 v0, 0x210, v131
	v_readfirstlane_b32 s28, v130
	s_lshr_b32 s9, s25, 6
	v_lshlrev_b32_e32 v171, 2, v129
	s_mul_i32 s30, s28, 0x820
	v_add_u32_e32 v172, s30, v171
	v_lshl_add_u32 v165, v129, 3, s28
	s_waitcnt lgkmcnt(0)
	s_barrier
	ds_read_b32 v116, v172 offset:39168
	ds_read_b32 v117, v172 offset:39428
	ds_read_b32 v118, v172 offset:39688
	ds_read_b32 v119, v172 offset:39948
	ds_read_b32 v120, v172 offset:40208
	ds_read_b32 v121, v172 offset:40468
	ds_read_b32 v122, v172 offset:40728
	ds_read_b32 v123, v172 offset:40988
	s_lshl_b32 s31, s28, 3
	s_sub_i32 s32, s9, s31
	s_cmp_lt_u32 s32, 2
	s_cselect_b32 s36, 0x461c4000, 0
	s_cmp_eq_u32 s31, 0
	s_cselect_b32 s36, 0x461c4000, s36
	s_cmp_ge_i32 s32, 0
	s_cselect_b64 s[48:49], -1, 0
	s_waitcnt lgkmcnt(7)
	v_add_f32_e32 v116, s36, v116
	v_cndmask_b32_e64 v116, v232, v116, s[48:49]
	ds_write_b32 v172, v116 offset:39168
	s_lshl_b32 s31, s28, 3
	s_add_u32 s31, s31, 1
	s_sub_i32 s32, s9, s31
	s_cmp_lt_u32 s32, 2
	s_cselect_b32 s36, 0x461c4000, 0
	s_cmp_eq_u32 s31, 0
	s_cselect_b32 s36, 0x461c4000, s36
	s_cmp_ge_i32 s32, 0
	s_cselect_b64 s[48:49], -1, 0
	s_waitcnt lgkmcnt(7)
	v_add_f32_e32 v117, s36, v117
	v_cndmask_b32_e64 v117, v232, v117, s[48:49]
	ds_write_b32 v172, v117 offset:39428
	s_lshl_b32 s31, s28, 3
	s_add_u32 s31, s31, 2
	s_sub_i32 s32, s9, s31
	s_cmp_lt_u32 s32, 2
	s_cselect_b32 s36, 0x461c4000, 0
	s_cmp_eq_u32 s31, 0
	s_cselect_b32 s36, 0x461c4000, s36
	s_cmp_ge_i32 s32, 0
	s_cselect_b64 s[48:49], -1, 0
	s_waitcnt lgkmcnt(7)
	v_add_f32_e32 v118, s36, v118
	v_cndmask_b32_e64 v118, v232, v118, s[48:49]
	ds_write_b32 v172, v118 offset:39688
	s_lshl_b32 s31, s28, 3
	s_add_u32 s31, s31, 3
	s_sub_i32 s32, s9, s31
	s_cmp_lt_u32 s32, 2
	s_cselect_b32 s36, 0x461c4000, 0
	s_cmp_eq_u32 s31, 0
	s_cselect_b32 s36, 0x461c4000, s36
	s_cmp_ge_i32 s32, 0
	s_cselect_b64 s[48:49], -1, 0
	s_waitcnt lgkmcnt(7)
	v_add_f32_e32 v119, s36, v119
	v_cndmask_b32_e64 v119, v232, v119, s[48:49]
	ds_write_b32 v172, v119 offset:39948
	s_lshl_b32 s31, s28, 3
	s_add_u32 s31, s31, 4
	s_sub_i32 s32, s9, s31
	s_cmp_lt_u32 s32, 2
	s_cselect_b32 s36, 0x461c4000, 0
	s_cmp_eq_u32 s31, 0
	s_cselect_b32 s36, 0x461c4000, s36
	s_cmp_ge_i32 s32, 0
	s_cselect_b64 s[48:49], -1, 0
	s_waitcnt lgkmcnt(7)
	v_add_f32_e32 v120, s36, v120
	v_cndmask_b32_e64 v120, v232, v120, s[48:49]
	ds_write_b32 v172, v120 offset:40208
	s_lshl_b32 s31, s28, 3
	s_add_u32 s31, s31, 5
	s_sub_i32 s32, s9, s31
	s_cmp_lt_u32 s32, 2
	s_cselect_b32 s36, 0x461c4000, 0
	s_cmp_eq_u32 s31, 0
	s_cselect_b32 s36, 0x461c4000, s36
	s_cmp_ge_i32 s32, 0
	s_cselect_b64 s[48:49], -1, 0
	s_waitcnt lgkmcnt(7)
	v_add_f32_e32 v121, s36, v121
	v_cndmask_b32_e64 v121, v232, v121, s[48:49]
	ds_write_b32 v172, v121 offset:40468
	s_lshl_b32 s31, s28, 3
	s_add_u32 s31, s31, 6
	s_sub_i32 s32, s9, s31
	s_cmp_lt_u32 s32, 2
	s_cselect_b32 s36, 0x461c4000, 0
	s_cmp_eq_u32 s31, 0
	s_cselect_b32 s36, 0x461c4000, s36
	s_cmp_ge_i32 s32, 0
	s_cselect_b64 s[48:49], -1, 0
	s_waitcnt lgkmcnt(7)
	v_add_f32_e32 v122, s36, v122
	v_cndmask_b32_e64 v122, v232, v122, s[48:49]
	ds_write_b32 v172, v122 offset:40728
	s_lshl_b32 s31, s28, 3
	s_add_u32 s31, s31, 7
	s_sub_i32 s32, s9, s31
	s_cmp_lt_u32 s32, 2
	s_cselect_b32 s36, 0x461c4000, 0
	s_cmp_eq_u32 s31, 0
	s_cselect_b32 s36, 0x461c4000, s36
	s_cmp_ge_i32 s32, 0
	s_cselect_b64 s[48:49], -1, 0
	s_waitcnt lgkmcnt(7)
	v_add_f32_e32 v123, s36, v123
	v_cndmask_b32_e64 v123, v232, v123, s[48:49]
	ds_write_b32 v172, v123 offset:40988
	s_waitcnt lgkmcnt(0)
	s_barrier
	ds_read_b32 v16, v171 offset:39168
	ds_read_b32 v17, v171 offset:39428
	ds_read_b32 v18, v171 offset:39688
	ds_read_b32 v19, v171 offset:39948
	ds_read_b32 v20, v171 offset:40208
	ds_read_b32 v21, v171 offset:40468
	ds_read_b32 v22, v171 offset:40728
	ds_read_b32 v23, v171 offset:40988
	v_mov_b32_e32 v156, 0
	v_mov_b32_e32 v157, 0
	v_mov_b32_e32 v158, 0
	v_mov_b32_e32 v159, 0
	v_mov_b32_e32 v160, 0
	v_mov_b32_e32 v161, 0
	v_mov_b32_e32 v162, 0
	v_mov_b32_e32 v163, 0
	ds_read_b32 v24, v171 offset:41248
	ds_read_b32 v25, v171 offset:41508
	ds_read_b32 v26, v171 offset:41768
	ds_read_b32 v27, v171 offset:42028
	ds_read_b32 v28, v171 offset:42288
	ds_read_b32 v29, v171 offset:42548
	ds_read_b32 v30, v171 offset:42808
	ds_read_b32 v31, v171 offset:43068
	s_cmp_lt_u32 0, s28
	s_cselect_b32 s31, 1, 0
	s_cmp_le_u32 0, s28
	s_cselect_b32 s32, 1, 0
	v_subrev_u32_e32 v140, s31, v116
	v_subrev_u32_e32 v141, s31, v117
	v_subrev_u32_e32 v142, s31, v118
	v_subrev_u32_e32 v143, s31, v119
	v_subrev_u32_e32 v144, s31, v120
	v_subrev_u32_e32 v145, s31, v121
	v_subrev_u32_e32 v146, s31, v122
	v_subrev_u32_e32 v147, s31, v123
	v_subrev_u32_e32 v148, s32, v116
	v_subrev_u32_e32 v149, s32, v117
	v_subrev_u32_e32 v150, s32, v118
	v_subrev_u32_e32 v151, s32, v119
	v_subrev_u32_e32 v152, s32, v120
	v_subrev_u32_e32 v153, s32, v121
	v_subrev_u32_e32 v154, s32, v122
	v_subrev_u32_e32 v155, s32, v123
	s_waitcnt lgkmcnt(8)
; DI void task_nsa(const P& p, int layer, int task, bf16_t* sm, int dm) {
;     ...
;     int rank = 0;
; #pragma unroll 4
;     for (int jp = 0; jp < 64; ++jp) {
;       const float sj = __int_as_float(__builtin_amdgcn_readlane(__float_as_int(score), jp));
;       rank += ((sj > score) || (sj == score && jp < j)) ? 1 : 0;
;     }
	v_cmp_gt_i32_e64 s[72:73], v16, v140
	v_cmp_gt_i32_e64 s[74:75], v16, v149
	v_cmp_gt_i32_e64 s[76:77], v16, v150
	v_addc_co_u32_e64 v156, s[42:43], 0, v156, s[72:73]
	v_cmp_gt_i32_e64 s[50:51], v16, v151
	v_addc_co_u32_e64 v157, s[42:43], 0, v157, s[74:75]
	v_cmp_gt_i32_e64 s[72:73], v16, v152
	v_addc_co_u32_e64 v158, s[42:43], 0, v158, s[76:77]
	v_cmp_gt_i32_e64 s[74:75], v16, v153
	v_addc_co_u32_e64 v159, s[42:43], 0, v159, s[50:51]
	v_cmp_gt_i32_e64 s[76:77], v16, v154
	v_addc_co_u32_e64 v160, s[42:43], 0, v160, s[72:73]
	v_cmp_gt_i32_e64 s[50:51], v16, v155
	v_addc_co_u32_e64 v161, s[42:43], 0, v161, s[74:75]
	v_cmp_gt_i32_e64 s[72:73], v17, v140
	v_addc_co_u32_e64 v162, s[42:43], 0, v162, s[76:77]
	v_cmp_gt_i32_e64 s[74:75], v17, v141
	v_addc_co_u32_e64 v163, s[42:43], 0, v163, s[50:51]
	v_cmp_gt_i32_e64 s[76:77], v17, v150
	v_addc_co_u32_e64 v156, s[42:43], 0, v156, s[72:73]
	v_cmp_gt_i32_e64 s[50:51], v17, v151
	v_addc_co_u32_e64 v157, s[42:43], 0, v157, s[74:75]
	v_cmp_gt_i32_e64 s[72:73], v17, v152
	v_addc_co_u32_e64 v158, s[42:43], 0, v158, s[76:77]
	v_cmp_gt_i32_e64 s[74:75], v17, v153
	v_addc_co_u32_e64 v159, s[42:43], 0, v159, s[50:51]
	v_cmp_gt_i32_e64 s[76:77], v17, v154
	v_addc_co_u32_e64 v160, s[42:43], 0, v160, s[72:73]
	v_cmp_gt_i32_e64 s[50:51], v17, v155
	v_addc_co_u32_e64 v161, s[42:43], 0, v161, s[74:75]
	v_cmp_gt_i32_e64 s[72:73], v18, v140
	v_addc_co_u32_e64 v162, s[42:43], 0, v162, s[76:77]
	v_cmp_gt_i32_e64 s[74:75], v18, v141
	v_addc_co_u32_e64 v163, s[42:43], 0, v163, s[50:51]
	v_cmp_gt_i32_e64 s[76:77], v18, v142
	v_addc_co_u32_e64 v156, s[42:43], 0, v156, s[72:73]
	v_cmp_gt_i32_e64 s[50:51], v18, v151
	v_addc_co_u32_e64 v157, s[42:43], 0, v157, s[74:75]
	v_cmp_gt_i32_e64 s[72:73], v18, v152
	v_addc_co_u32_e64 v158, s[42:43], 0, v158, s[76:77]
	v_cmp_gt_i32_e64 s[74:75], v18, v153
	v_addc_co_u32_e64 v159, s[42:43], 0, v159, s[50:51]
	v_cmp_gt_i32_e64 s[76:77], v18, v154
	v_addc_co_u32_e64 v160, s[42:43], 0, v160, s[72:73]
	v_cmp_gt_i32_e64 s[50:51], v18, v155
	v_addc_co_u32_e64 v161, s[42:43], 0, v161, s[74:75]
	v_cmp_gt_i32_e64 s[72:73], v19, v140
	v_addc_co_u32_e64 v162, s[42:43], 0, v162, s[76:77]
	v_cmp_gt_i32_e64 s[74:75], v19, v141
	v_addc_co_u32_e64 v163, s[42:43], 0, v163, s[50:51]
	v_cmp_gt_i32_e64 s[76:77], v19, v142
	v_addc_co_u32_e64 v156, s[42:43], 0, v156, s[72:73]
	v_cmp_gt_i32_e64 s[50:51], v19, v143
	v_addc_co_u32_e64 v157, s[42:43], 0, v157, s[74:75]
	v_cmp_gt_i32_e64 s[72:73], v19, v152
	v_addc_co_u32_e64 v158, s[42:43], 0, v158, s[76:77]
	v_cmp_gt_i32_e64 s[74:75], v19, v153
	v_addc_co_u32_e64 v159, s[42:43], 0, v159, s[50:51]
	v_cmp_gt_i32_e64 s[76:77], v19, v154
	v_addc_co_u32_e64 v160, s[42:43], 0, v160, s[72:73]
	v_cmp_gt_i32_e64 s[50:51], v19, v155
	v_addc_co_u32_e64 v161, s[42:43], 0, v161, s[74:75]
	v_cmp_gt_i32_e64 s[72:73], v20, v140
	v_addc_co_u32_e64 v162, s[42:43], 0, v162, s[76:77]
	v_cmp_gt_i32_e64 s[74:75], v20, v141
	v_addc_co_u32_e64 v163, s[42:43], 0, v163, s[50:51]
	v_cmp_gt_i32_e64 s[76:77], v20, v142
	v_addc_co_u32_e64 v156, s[42:43], 0, v156, s[72:73]
	v_cmp_gt_i32_e64 s[50:51], v20, v143
	v_addc_co_u32_e64 v157, s[42:43], 0, v157, s[74:75]
	v_cmp_gt_i32_e64 s[72:73], v20, v144
	v_addc_co_u32_e64 v158, s[42:43], 0, v158, s[76:77]
	v_cmp_gt_i32_e64 s[74:75], v20, v153
	v_addc_co_u32_e64 v159, s[42:43], 0, v159, s[50:51]
	v_cmp_gt_i32_e64 s[76:77], v20, v154
	v_addc_co_u32_e64 v160, s[42:43], 0, v160, s[72:73]
	v_cmp_gt_i32_e64 s[50:51], v20, v155
	v_addc_co_u32_e64 v161, s[42:43], 0, v161, s[74:75]
	v_cmp_gt_i32_e64 s[72:73], v21, v140
	v_addc_co_u32_e64 v162, s[42:43], 0, v162, s[76:77]
	v_cmp_gt_i32_e64 s[74:75], v21, v141
	v_addc_co_u32_e64 v163, s[42:43], 0, v163, s[50:51]
	v_cmp_gt_i32_e64 s[76:77], v21, v142
	v_addc_co_u32_e64 v156, s[42:43], 0, v156, s[72:73]
	v_cmp_gt_i32_e64 s[50:51], v21, v143
	v_addc_co_u32_e64 v157, s[42:43], 0, v157, s[74:75]
	v_cmp_gt_i32_e64 s[72:73], v21, v144
	v_addc_co_u32_e64 v158, s[42:43], 0, v158, s[76:77]
	v_cmp_gt_i32_e64 s[74:75], v21, v145
	v_addc_co_u32_e64 v159, s[42:43], 0, v159, s[50:51]
	v_cmp_gt_i32_e64 s[76:77], v21, v154
	v_addc_co_u32_e64 v160, s[42:43], 0, v160, s[72:73]
	v_cmp_gt_i32_e64 s[50:51], v21, v155
	v_addc_co_u32_e64 v161, s[42:43], 0, v161, s[74:75]
	v_cmp_gt_i32_e64 s[72:73], v22, v140
	v_addc_co_u32_e64 v162, s[42:43], 0, v162, s[76:77]
	v_cmp_gt_i32_e64 s[74:75], v22, v141
	v_addc_co_u32_e64 v163, s[42:43], 0, v163, s[50:51]
	v_cmp_gt_i32_e64 s[76:77], v22, v142
	v_addc_co_u32_e64 v156, s[42:43], 0, v156, s[72:73]
	v_cmp_gt_i32_e64 s[50:51], v22, v143
	v_addc_co_u32_e64 v157, s[42:43], 0, v157, s[74:75]
	v_cmp_gt_i32_e64 s[72:73], v22, v144
	v_addc_co_u32_e64 v158, s[42:43], 0, v158, s[76:77]
	v_cmp_gt_i32_e64 s[74:75], v22, v145
	v_addc_co_u32_e64 v159, s[42:43], 0, v159, s[50:51]
	v_cmp_gt_i32_e64 s[76:77], v22, v146
	v_addc_co_u32_e64 v160, s[42:43], 0, v160, s[72:73]
	v_cmp_gt_i32_e64 s[50:51], v22, v155
	v_addc_co_u32_e64 v161, s[42:43], 0, v161, s[74:75]
	v_cmp_gt_i32_e64 s[72:73], v23, v140
	v_addc_co_u32_e64 v162, s[42:43], 0, v162, s[76:77]
	v_cmp_gt_i32_e64 s[74:75], v23, v141
	v_addc_co_u32_e64 v163, s[42:43], 0, v163, s[50:51]
	v_cmp_gt_i32_e64 s[76:77], v23, v142
	v_addc_co_u32_e64 v156, s[42:43], 0, v156, s[72:73]
	v_cmp_gt_i32_e64 s[50:51], v23, v143
	v_addc_co_u32_e64 v157, s[42:43], 0, v157, s[74:75]
	v_cmp_gt_i32_e64 s[72:73], v23, v144
	v_addc_co_u32_e64 v158, s[42:43], 0, v158, s[76:77]
	v_cmp_gt_i32_e64 s[74:75], v23, v145
	v_addc_co_u32_e64 v159, s[42:43], 0, v159, s[50:51]
	v_cmp_gt_i32_e64 s[76:77], v23, v146
	v_addc_co_u32_e64 v160, s[42:43], 0, v160, s[72:73]
	v_cmp_gt_i32_e64 s[50:51], v23, v147
	v_addc_co_u32_e64 v161, s[42:43], 0, v161, s[74:75]
	v_addc_co_u32_e64 v162, s[42:43], 0, v162, s[76:77]
	v_addc_co_u32_e64 v163, s[42:43], 0, v163, s[50:51]
	s_cmp_gt_u32 8, s9
	s_cbranch_scc1 .Ltopk_oct_done
; DI void task_nsa(const P& p, int layer, int task, bf16_t* sm, int dm) {
;     ...
;     int rank = 0;
; #pragma unroll 4
;     for (int jp = 0; jp < 64; ++jp) {
;       const float sj = __int_as_float(__builtin_amdgcn_readlane(__float_as_int(score), jp));
;       rank += ((sj > score) || (sj == score && jp < j)) ? 1 : 0;
;     }
	ds_read_b32 v32, v171 offset:43328
	ds_read_b32 v33, v171 offset:43588
	ds_read_b32 v34, v171 offset:43848
	ds_read_b32 v35, v171 offset:44108
	ds_read_b32 v36, v171 offset:44368
	ds_read_b32 v37, v171 offset:44628
	ds_read_b32 v38, v171 offset:44888
	ds_read_b32 v39, v171 offset:45148
	s_cmp_lt_u32 1, s28
	s_cselect_b32 s31, 1, 0
	s_cmp_le_u32 1, s28
	s_cselect_b32 s32, 1, 0
	v_subrev_u32_e32 v140, s31, v116
	v_subrev_u32_e32 v141, s31, v117
	v_subrev_u32_e32 v142, s31, v118
	v_subrev_u32_e32 v143, s31, v119
	v_subrev_u32_e32 v144, s31, v120
	v_subrev_u32_e32 v145, s31, v121
	v_subrev_u32_e32 v146, s31, v122
	v_subrev_u32_e32 v147, s31, v123
	v_subrev_u32_e32 v148, s32, v116
	v_subrev_u32_e32 v149, s32, v117
	v_subrev_u32_e32 v150, s32, v118
	v_subrev_u32_e32 v151, s32, v119
	v_subrev_u32_e32 v152, s32, v120
	v_subrev_u32_e32 v153, s32, v121
	v_subrev_u32_e32 v154, s32, v122
	v_subrev_u32_e32 v155, s32, v123
	s_waitcnt lgkmcnt(8)
	v_cmp_gt_i32_e64 s[72:73], v24, v140
	v_cmp_gt_i32_e64 s[74:75], v24, v149
	v_cmp_gt_i32_e64 s[76:77], v24, v150
	v_addc_co_u32_e64 v156, s[42:43], 0, v156, s[72:73]
	v_cmp_gt_i32_e64 s[50:51], v24, v151
	v_addc_co_u32_e64 v157, s[42:43], 0, v157, s[74:75]
	v_cmp_gt_i32_e64 s[72:73], v24, v152
	v_addc_co_u32_e64 v158, s[42:43], 0, v158, s[76:77]
	v_cmp_gt_i32_e64 s[74:75], v24, v153
	v_addc_co_u32_e64 v159, s[42:43], 0, v159, s[50:51]
	v_cmp_gt_i32_e64 s[76:77], v24, v154
	v_addc_co_u32_e64 v160, s[42:43], 0, v160, s[72:73]
	v_cmp_gt_i32_e64 s[50:51], v24, v155
	v_addc_co_u32_e64 v161, s[42:43], 0, v161, s[74:75]
	v_cmp_gt_i32_e64 s[72:73], v25, v140
	v_addc_co_u32_e64 v162, s[42:43], 0, v162, s[76:77]
	v_cmp_gt_i32_e64 s[74:75], v25, v141
	v_addc_co_u32_e64 v163, s[42:43], 0, v163, s[50:51]
	v_cmp_gt_i32_e64 s[76:77], v25, v150
	v_addc_co_u32_e64 v156, s[42:43], 0, v156, s[72:73]
	v_cmp_gt_i32_e64 s[50:51], v25, v151
	v_addc_co_u32_e64 v157, s[42:43], 0, v157, s[74:75]
	v_cmp_gt_i32_e64 s[72:73], v25, v152
	v_addc_co_u32_e64 v158, s[42:43], 0, v158, s[76:77]
	v_cmp_gt_i32_e64 s[74:75], v25, v153
	v_addc_co_u32_e64 v159, s[42:43], 0, v159, s[50:51]
	v_cmp_gt_i32_e64 s[76:77], v25, v154
	v_addc_co_u32_e64 v160, s[42:43], 0, v160, s[72:73]
	v_cmp_gt_i32_e64 s[50:51], v25, v155
	v_addc_co_u32_e64 v161, s[42:43], 0, v161, s[74:75]
	v_cmp_gt_i32_e64 s[72:73], v26, v140
	v_addc_co_u32_e64 v162, s[42:43], 0, v162, s[76:77]
	v_cmp_gt_i32_e64 s[74:75], v26, v141
	v_addc_co_u32_e64 v163, s[42:43], 0, v163, s[50:51]
	v_cmp_gt_i32_e64 s[76:77], v26, v142
	v_addc_co_u32_e64 v156, s[42:43], 0, v156, s[72:73]
	v_cmp_gt_i32_e64 s[50:51], v26, v151
	v_addc_co_u32_e64 v157, s[42:43], 0, v157, s[74:75]
	v_cmp_gt_i32_e64 s[72:73], v26, v152
	v_addc_co_u32_e64 v158, s[42:43], 0, v158, s[76:77]
	v_cmp_gt_i32_e64 s[74:75], v26, v153
	v_addc_co_u32_e64 v159, s[42:43], 0, v159, s[50:51]
	v_cmp_gt_i32_e64 s[76:77], v26, v154
	v_addc_co_u32_e64 v160, s[42:43], 0, v160, s[72:73]
	v_cmp_gt_i32_e64 s[50:51], v26, v155
	v_addc_co_u32_e64 v161, s[42:43], 0, v161, s[74:75]
	v_cmp_gt_i32_e64 s[72:73], v27, v140
	v_addc_co_u32_e64 v162, s[42:43], 0, v162, s[76:77]
	v_cmp_gt_i32_e64 s[74:75], v27, v141
	v_addc_co_u32_e64 v163, s[42:43], 0, v163, s[50:51]
	v_cmp_gt_i32_e64 s[76:77], v27, v142
	v_addc_co_u32_e64 v156, s[42:43], 0, v156, s[72:73]
	v_cmp_gt_i32_e64 s[50:51], v27, v143
	v_addc_co_u32_e64 v157, s[42:43], 0, v157, s[74:75]
	v_cmp_gt_i32_e64 s[72:73], v27, v152
	v_addc_co_u32_e64 v158, s[42:43], 0, v158, s[76:77]
	v_cmp_gt_i32_e64 s[74:75], v27, v153
	v_addc_co_u32_e64 v159, s[42:43], 0, v159, s[50:51]
	v_cmp_gt_i32_e64 s[76:77], v27, v154
	v_addc_co_u32_e64 v160, s[42:43], 0, v160, s[72:73]
	v_cmp_gt_i32_e64 s[50:51], v27, v155
	v_addc_co_u32_e64 v161, s[42:43], 0, v161, s[74:75]
	v_cmp_gt_i32_e64 s[72:73], v28, v140
	v_addc_co_u32_e64 v162, s[42:43], 0, v162, s[76:77]
	v_cmp_gt_i32_e64 s[74:75], v28, v141
	v_addc_co_u32_e64 v163, s[42:43], 0, v163, s[50:51]
	v_cmp_gt_i32_e64 s[76:77], v28, v142
	v_addc_co_u32_e64 v156, s[42:43], 0, v156, s[72:73]
	v_cmp_gt_i32_e64 s[50:51], v28, v143
	v_addc_co_u32_e64 v157, s[42:43], 0, v157, s[74:75]
	v_cmp_gt_i32_e64 s[72:73], v28, v144
	v_addc_co_u32_e64 v158, s[42:43], 0, v158, s[76:77]
	v_cmp_gt_i32_e64 s[74:75], v28, v153
	v_addc_co_u32_e64 v159, s[42:43], 0, v159, s[50:51]
	v_cmp_gt_i32_e64 s[76:77], v28, v154
	v_addc_co_u32_e64 v160, s[42:43], 0, v160, s[72:73]
	v_cmp_gt_i32_e64 s[50:51], v28, v155
	v_addc_co_u32_e64 v161, s[42:43], 0, v161, s[74:75]
	v_cmp_gt_i32_e64 s[72:73], v29, v140
	v_addc_co_u32_e64 v162, s[42:43], 0, v162, s[76:77]
	v_cmp_gt_i32_e64 s[74:75], v29, v141
	v_addc_co_u32_e64 v163, s[42:43], 0, v163, s[50:51]
	v_cmp_gt_i32_e64 s[76:77], v29, v142
	v_addc_co_u32_e64 v156, s[42:43], 0, v156, s[72:73]
	v_cmp_gt_i32_e64 s[50:51], v29, v143
	v_addc_co_u32_e64 v157, s[42:43], 0, v157, s[74:75]
	v_cmp_gt_i32_e64 s[72:73], v29, v144
	v_addc_co_u32_e64 v158, s[42:43], 0, v158, s[76:77]
	v_cmp_gt_i32_e64 s[74:75], v29, v145
	v_addc_co_u32_e64 v159, s[42:43], 0, v159, s[50:51]
	v_cmp_gt_i32_e64 s[76:77], v29, v154
	v_addc_co_u32_e64 v160, s[42:43], 0, v160, s[72:73]
	v_cmp_gt_i32_e64 s[50:51], v29, v155
	v_addc_co_u32_e64 v161, s[42:43], 0, v161, s[74:75]
	v_cmp_gt_i32_e64 s[72:73], v30, v140
	v_addc_co_u32_e64 v162, s[42:43], 0, v162, s[76:77]
	v_cmp_gt_i32_e64 s[74:75], v30, v141
	v_addc_co_u32_e64 v163, s[42:43], 0, v163, s[50:51]
	v_cmp_gt_i32_e64 s[76:77], v30, v142
	v_addc_co_u32_e64 v156, s[42:43], 0, v156, s[72:73]
	v_cmp_gt_i32_e64 s[50:51], v30, v143
	v_addc_co_u32_e64 v157, s[42:43], 0, v157, s[74:75]
	v_cmp_gt_i32_e64 s[72:73], v30, v144
	v_addc_co_u32_e64 v158, s[42:43], 0, v158, s[76:77]
	v_cmp_gt_i32_e64 s[74:75], v30, v145
	v_addc_co_u32_e64 v159, s[42:43], 0, v159, s[50:51]
	v_cmp_gt_i32_e64 s[76:77], v30, v146
	v_addc_co_u32_e64 v160, s[42:43], 0, v160, s[72:73]
	v_cmp_gt_i32_e64 s[50:51], v30, v155
	v_addc_co_u32_e64 v161, s[42:43], 0, v161, s[74:75]
	v_cmp_gt_i32_e64 s[72:73], v31, v140
	v_addc_co_u32_e64 v162, s[42:43], 0, v162, s[76:77]
	v_cmp_gt_i32_e64 s[74:75], v31, v141
	v_addc_co_u32_e64 v163, s[42:43], 0, v163, s[50:51]
	v_cmp_gt_i32_e64 s[76:77], v31, v142
	v_addc_co_u32_e64 v156, s[42:43], 0, v156, s[72:73]
	v_cmp_gt_i32_e64 s[50:51], v31, v143
	v_addc_co_u32_e64 v157, s[42:43], 0, v157, s[74:75]
	v_cmp_gt_i32_e64 s[72:73], v31, v144
	v_addc_co_u32_e64 v158, s[42:43], 0, v158, s[76:77]
	v_cmp_gt_i32_e64 s[74:75], v31, v145
	v_addc_co_u32_e64 v159, s[42:43], 0, v159, s[50:51]
	v_cmp_gt_i32_e64 s[76:77], v31, v146
	v_addc_co_u32_e64 v160, s[42:43], 0, v160, s[72:73]
	v_cmp_gt_i32_e64 s[50:51], v31, v147
	v_addc_co_u32_e64 v161, s[42:43], 0, v161, s[74:75]
	v_addc_co_u32_e64 v162, s[42:43], 0, v162, s[76:77]
	v_addc_co_u32_e64 v163, s[42:43], 0, v163, s[50:51]
	s_cmp_gt_u32 16, s9
	s_cbranch_scc1 .Ltopk_oct_done
; DI void task_nsa(const P& p, int layer, int task, bf16_t* sm, int dm) {
;     ...
;     int rank = 0;
; #pragma unroll 4
;     for (int jp = 0; jp < 64; ++jp) {
;       const float sj = __int_as_float(__builtin_amdgcn_readlane(__float_as_int(score), jp));
;       rank += ((sj > score) || (sj == score && jp < j)) ? 1 : 0;
;     }
	ds_read_b32 v40, v171 offset:45408
	ds_read_b32 v41, v171 offset:45668
	ds_read_b32 v42, v171 offset:45928
	ds_read_b32 v43, v171 offset:46188
	ds_read_b32 v44, v171 offset:46448
	ds_read_b32 v45, v171 offset:46708
	ds_read_b32 v46, v171 offset:46968
	ds_read_b32 v47, v171 offset:47228
	s_cmp_lt_u32 2, s28
	s_cselect_b32 s31, 1, 0
	s_cmp_le_u32 2, s28
	s_cselect_b32 s32, 1, 0
	v_subrev_u32_e32 v140, s31, v116
	v_subrev_u32_e32 v141, s31, v117
	v_subrev_u32_e32 v142, s31, v118
	v_subrev_u32_e32 v143, s31, v119
	v_subrev_u32_e32 v144, s31, v120
	v_subrev_u32_e32 v145, s31, v121
	v_subrev_u32_e32 v146, s31, v122
	v_subrev_u32_e32 v147, s31, v123
	v_subrev_u32_e32 v148, s32, v116
	v_subrev_u32_e32 v149, s32, v117
	v_subrev_u32_e32 v150, s32, v118
	v_subrev_u32_e32 v151, s32, v119
	v_subrev_u32_e32 v152, s32, v120
	v_subrev_u32_e32 v153, s32, v121
	v_subrev_u32_e32 v154, s32, v122
	v_subrev_u32_e32 v155, s32, v123
	s_waitcnt lgkmcnt(8)
	v_cmp_gt_i32_e64 s[72:73], v32, v140
	v_cmp_gt_i32_e64 s[74:75], v32, v149
	v_cmp_gt_i32_e64 s[76:77], v32, v150
	v_addc_co_u32_e64 v156, s[42:43], 0, v156, s[72:73]
	v_cmp_gt_i32_e64 s[50:51], v32, v151
	v_addc_co_u32_e64 v157, s[42:43], 0, v157, s[74:75]
	v_cmp_gt_i32_e64 s[72:73], v32, v152
	v_addc_co_u32_e64 v158, s[42:43], 0, v158, s[76:77]
	v_cmp_gt_i32_e64 s[74:75], v32, v153
	v_addc_co_u32_e64 v159, s[42:43], 0, v159, s[50:51]
	v_cmp_gt_i32_e64 s[76:77], v32, v154
	v_addc_co_u32_e64 v160, s[42:43], 0, v160, s[72:73]
	v_cmp_gt_i32_e64 s[50:51], v32, v155
	v_addc_co_u32_e64 v161, s[42:43], 0, v161, s[74:75]
	v_cmp_gt_i32_e64 s[72:73], v33, v140
	v_addc_co_u32_e64 v162, s[42:43], 0, v162, s[76:77]
	v_cmp_gt_i32_e64 s[74:75], v33, v141
	v_addc_co_u32_e64 v163, s[42:43], 0, v163, s[50:51]
	v_cmp_gt_i32_e64 s[76:77], v33, v150
	v_addc_co_u32_e64 v156, s[42:43], 0, v156, s[72:73]
	v_cmp_gt_i32_e64 s[50:51], v33, v151
	v_addc_co_u32_e64 v157, s[42:43], 0, v157, s[74:75]
	v_cmp_gt_i32_e64 s[72:73], v33, v152
	v_addc_co_u32_e64 v158, s[42:43], 0, v158, s[76:77]
	v_cmp_gt_i32_e64 s[74:75], v33, v153
	v_addc_co_u32_e64 v159, s[42:43], 0, v159, s[50:51]
	v_cmp_gt_i32_e64 s[76:77], v33, v154
	v_addc_co_u32_e64 v160, s[42:43], 0, v160, s[72:73]
	v_cmp_gt_i32_e64 s[50:51], v33, v155
	v_addc_co_u32_e64 v161, s[42:43], 0, v161, s[74:75]
	v_cmp_gt_i32_e64 s[72:73], v34, v140
	v_addc_co_u32_e64 v162, s[42:43], 0, v162, s[76:77]
	v_cmp_gt_i32_e64 s[74:75], v34, v141
	v_addc_co_u32_e64 v163, s[42:43], 0, v163, s[50:51]
	v_cmp_gt_i32_e64 s[76:77], v34, v142
	v_addc_co_u32_e64 v156, s[42:43], 0, v156, s[72:73]
	v_cmp_gt_i32_e64 s[50:51], v34, v151
	v_addc_co_u32_e64 v157, s[42:43], 0, v157, s[74:75]
	v_cmp_gt_i32_e64 s[72:73], v34, v152
	v_addc_co_u32_e64 v158, s[42:43], 0, v158, s[76:77]
	v_cmp_gt_i32_e64 s[74:75], v34, v153
	v_addc_co_u32_e64 v159, s[42:43], 0, v159, s[50:51]
	v_cmp_gt_i32_e64 s[76:77], v34, v154
	v_addc_co_u32_e64 v160, s[42:43], 0, v160, s[72:73]
	v_cmp_gt_i32_e64 s[50:51], v34, v155
	v_addc_co_u32_e64 v161, s[42:43], 0, v161, s[74:75]
	v_cmp_gt_i32_e64 s[72:73], v35, v140
	v_addc_co_u32_e64 v162, s[42:43], 0, v162, s[76:77]
	v_cmp_gt_i32_e64 s[74:75], v35, v141
	v_addc_co_u32_e64 v163, s[42:43], 0, v163, s[50:51]
	v_cmp_gt_i32_e64 s[76:77], v35, v142
	v_addc_co_u32_e64 v156, s[42:43], 0, v156, s[72:73]
	v_cmp_gt_i32_e64 s[50:51], v35, v143
	v_addc_co_u32_e64 v157, s[42:43], 0, v157, s[74:75]
	v_cmp_gt_i32_e64 s[72:73], v35, v152
	v_addc_co_u32_e64 v158, s[42:43], 0, v158, s[76:77]
	v_cmp_gt_i32_e64 s[74:75], v35, v153
	v_addc_co_u32_e64 v159, s[42:43], 0, v159, s[50:51]
	v_cmp_gt_i32_e64 s[76:77], v35, v154
	v_addc_co_u32_e64 v160, s[42:43], 0, v160, s[72:73]
	v_cmp_gt_i32_e64 s[50:51], v35, v155
	v_addc_co_u32_e64 v161, s[42:43], 0, v161, s[74:75]
	v_cmp_gt_i32_e64 s[72:73], v36, v140
	v_addc_co_u32_e64 v162, s[42:43], 0, v162, s[76:77]
	v_cmp_gt_i32_e64 s[74:75], v36, v141
	v_addc_co_u32_e64 v163, s[42:43], 0, v163, s[50:51]
	v_cmp_gt_i32_e64 s[76:77], v36, v142
	v_addc_co_u32_e64 v156, s[42:43], 0, v156, s[72:73]
	v_cmp_gt_i32_e64 s[50:51], v36, v143
	v_addc_co_u32_e64 v157, s[42:43], 0, v157, s[74:75]
	v_cmp_gt_i32_e64 s[72:73], v36, v144
	v_addc_co_u32_e64 v158, s[42:43], 0, v158, s[76:77]
	v_cmp_gt_i32_e64 s[74:75], v36, v153
	v_addc_co_u32_e64 v159, s[42:43], 0, v159, s[50:51]
	v_cmp_gt_i32_e64 s[76:77], v36, v154
	v_addc_co_u32_e64 v160, s[42:43], 0, v160, s[72:73]
	v_cmp_gt_i32_e64 s[50:51], v36, v155
	v_addc_co_u32_e64 v161, s[42:43], 0, v161, s[74:75]
	v_cmp_gt_i32_e64 s[72:73], v37, v140
	v_addc_co_u32_e64 v162, s[42:43], 0, v162, s[76:77]
	v_cmp_gt_i32_e64 s[74:75], v37, v141
	v_addc_co_u32_e64 v163, s[42:43], 0, v163, s[50:51]
	v_cmp_gt_i32_e64 s[76:77], v37, v142
	v_addc_co_u32_e64 v156, s[42:43], 0, v156, s[72:73]
	v_cmp_gt_i32_e64 s[50:51], v37, v143
	v_addc_co_u32_e64 v157, s[42:43], 0, v157, s[74:75]
	v_cmp_gt_i32_e64 s[72:73], v37, v144
	v_addc_co_u32_e64 v158, s[42:43], 0, v158, s[76:77]
	v_cmp_gt_i32_e64 s[74:75], v37, v145
	v_addc_co_u32_e64 v159, s[42:43], 0, v159, s[50:51]
	v_cmp_gt_i32_e64 s[76:77], v37, v154
	v_addc_co_u32_e64 v160, s[42:43], 0, v160, s[72:73]
	v_cmp_gt_i32_e64 s[50:51], v37, v155
	v_addc_co_u32_e64 v161, s[42:43], 0, v161, s[74:75]
	v_cmp_gt_i32_e64 s[72:73], v38, v140
	v_addc_co_u32_e64 v162, s[42:43], 0, v162, s[76:77]
	v_cmp_gt_i32_e64 s[74:75], v38, v141
	v_addc_co_u32_e64 v163, s[42:43], 0, v163, s[50:51]
	v_cmp_gt_i32_e64 s[76:77], v38, v142
	v_addc_co_u32_e64 v156, s[42:43], 0, v156, s[72:73]
	v_cmp_gt_i32_e64 s[50:51], v38, v143
	v_addc_co_u32_e64 v157, s[42:43], 0, v157, s[74:75]
	v_cmp_gt_i32_e64 s[72:73], v38, v144
	v_addc_co_u32_e64 v158, s[42:43], 0, v158, s[76:77]
	v_cmp_gt_i32_e64 s[74:75], v38, v145
	v_addc_co_u32_e64 v159, s[42:43], 0, v159, s[50:51]
	v_cmp_gt_i32_e64 s[76:77], v38, v146
	v_addc_co_u32_e64 v160, s[42:43], 0, v160, s[72:73]
	v_cmp_gt_i32_e64 s[50:51], v38, v155
	v_addc_co_u32_e64 v161, s[42:43], 0, v161, s[74:75]
	v_cmp_gt_i32_e64 s[72:73], v39, v140
	v_addc_co_u32_e64 v162, s[42:43], 0, v162, s[76:77]
	v_cmp_gt_i32_e64 s[74:75], v39, v141
	v_addc_co_u32_e64 v163, s[42:43], 0, v163, s[50:51]
	v_cmp_gt_i32_e64 s[76:77], v39, v142
	v_addc_co_u32_e64 v156, s[42:43], 0, v156, s[72:73]
	v_cmp_gt_i32_e64 s[50:51], v39, v143
	v_addc_co_u32_e64 v157, s[42:43], 0, v157, s[74:75]
	v_cmp_gt_i32_e64 s[72:73], v39, v144
	v_addc_co_u32_e64 v158, s[42:43], 0, v158, s[76:77]
	v_cmp_gt_i32_e64 s[74:75], v39, v145
	v_addc_co_u32_e64 v159, s[42:43], 0, v159, s[50:51]
	v_cmp_gt_i32_e64 s[76:77], v39, v146
	v_addc_co_u32_e64 v160, s[42:43], 0, v160, s[72:73]
	v_cmp_gt_i32_e64 s[50:51], v39, v147
	v_addc_co_u32_e64 v161, s[42:43], 0, v161, s[74:75]
	v_addc_co_u32_e64 v162, s[42:43], 0, v162, s[76:77]
	v_addc_co_u32_e64 v163, s[42:43], 0, v163, s[50:51]
	s_cmp_gt_u32 24, s9
	s_cbranch_scc1 .Ltopk_oct_done
; DI void task_nsa(const P& p, int layer, int task, bf16_t* sm, int dm) {
;     ...
;     int rank = 0;
; #pragma unroll 4
;     for (int jp = 0; jp < 64; ++jp) {
;       const float sj = __int_as_float(__builtin_amdgcn_readlane(__float_as_int(score), jp));
;       rank += ((sj > score) || (sj == score && jp < j)) ? 1 : 0;
;     }
	ds_read_b32 v48, v171 offset:47488
	ds_read_b32 v49, v171 offset:47748
	ds_read_b32 v50, v171 offset:48008
	ds_read_b32 v51, v171 offset:48268
	ds_read_b32 v52, v171 offset:48528
	ds_read_b32 v53, v171 offset:48788
	ds_read_b32 v54, v171 offset:49048
	ds_read_b32 v55, v171 offset:49308
	s_cmp_lt_u32 3, s28
	s_cselect_b32 s31, 1, 0
	s_cmp_le_u32 3, s28
	s_cselect_b32 s32, 1, 0
	v_subrev_u32_e32 v140, s31, v116
	v_subrev_u32_e32 v141, s31, v117
	v_subrev_u32_e32 v142, s31, v118
	v_subrev_u32_e32 v143, s31, v119
	v_subrev_u32_e32 v144, s31, v120
	v_subrev_u32_e32 v145, s31, v121
	v_subrev_u32_e32 v146, s31, v122
	v_subrev_u32_e32 v147, s31, v123
	v_subrev_u32_e32 v148, s32, v116
	v_subrev_u32_e32 v149, s32, v117
	v_subrev_u32_e32 v150, s32, v118
	v_subrev_u32_e32 v151, s32, v119
	v_subrev_u32_e32 v152, s32, v120
	v_subrev_u32_e32 v153, s32, v121
	v_subrev_u32_e32 v154, s32, v122
	v_subrev_u32_e32 v155, s32, v123
	s_waitcnt lgkmcnt(8)
	v_cmp_gt_i32_e64 s[72:73], v40, v140
	v_cmp_gt_i32_e64 s[74:75], v40, v149
	v_cmp_gt_i32_e64 s[76:77], v40, v150
	v_addc_co_u32_e64 v156, s[42:43], 0, v156, s[72:73]
	v_cmp_gt_i32_e64 s[50:51], v40, v151
	v_addc_co_u32_e64 v157, s[42:43], 0, v157, s[74:75]
	v_cmp_gt_i32_e64 s[72:73], v40, v152
	v_addc_co_u32_e64 v158, s[42:43], 0, v158, s[76:77]
	v_cmp_gt_i32_e64 s[74:75], v40, v153
	v_addc_co_u32_e64 v159, s[42:43], 0, v159, s[50:51]
	v_cmp_gt_i32_e64 s[76:77], v40, v154
	v_addc_co_u32_e64 v160, s[42:43], 0, v160, s[72:73]
	v_cmp_gt_i32_e64 s[50:51], v40, v155
	v_addc_co_u32_e64 v161, s[42:43], 0, v161, s[74:75]
	v_cmp_gt_i32_e64 s[72:73], v41, v140
	v_addc_co_u32_e64 v162, s[42:43], 0, v162, s[76:77]
	v_cmp_gt_i32_e64 s[74:75], v41, v141
	v_addc_co_u32_e64 v163, s[42:43], 0, v163, s[50:51]
	v_cmp_gt_i32_e64 s[76:77], v41, v150
	v_addc_co_u32_e64 v156, s[42:43], 0, v156, s[72:73]
	v_cmp_gt_i32_e64 s[50:51], v41, v151
	v_addc_co_u32_e64 v157, s[42:43], 0, v157, s[74:75]
	v_cmp_gt_i32_e64 s[72:73], v41, v152
	v_addc_co_u32_e64 v158, s[42:43], 0, v158, s[76:77]
	v_cmp_gt_i32_e64 s[74:75], v41, v153
	v_addc_co_u32_e64 v159, s[42:43], 0, v159, s[50:51]
	v_cmp_gt_i32_e64 s[76:77], v41, v154
	v_addc_co_u32_e64 v160, s[42:43], 0, v160, s[72:73]
	v_cmp_gt_i32_e64 s[50:51], v41, v155
	v_addc_co_u32_e64 v161, s[42:43], 0, v161, s[74:75]
	v_cmp_gt_i32_e64 s[72:73], v42, v140
	v_addc_co_u32_e64 v162, s[42:43], 0, v162, s[76:77]
	v_cmp_gt_i32_e64 s[74:75], v42, v141
	v_addc_co_u32_e64 v163, s[42:43], 0, v163, s[50:51]
	v_cmp_gt_i32_e64 s[76:77], v42, v142
	v_addc_co_u32_e64 v156, s[42:43], 0, v156, s[72:73]
	v_cmp_gt_i32_e64 s[50:51], v42, v151
	v_addc_co_u32_e64 v157, s[42:43], 0, v157, s[74:75]
	v_cmp_gt_i32_e64 s[72:73], v42, v152
	v_addc_co_u32_e64 v158, s[42:43], 0, v158, s[76:77]
	v_cmp_gt_i32_e64 s[74:75], v42, v153
	v_addc_co_u32_e64 v159, s[42:43], 0, v159, s[50:51]
	v_cmp_gt_i32_e64 s[76:77], v42, v154
	v_addc_co_u32_e64 v160, s[42:43], 0, v160, s[72:73]
	v_cmp_gt_i32_e64 s[50:51], v42, v155
	v_addc_co_u32_e64 v161, s[42:43], 0, v161, s[74:75]
	v_cmp_gt_i32_e64 s[72:73], v43, v140
	v_addc_co_u32_e64 v162, s[42:43], 0, v162, s[76:77]
	v_cmp_gt_i32_e64 s[74:75], v43, v141
	v_addc_co_u32_e64 v163, s[42:43], 0, v163, s[50:51]
	v_cmp_gt_i32_e64 s[76:77], v43, v142
	v_addc_co_u32_e64 v156, s[42:43], 0, v156, s[72:73]
	v_cmp_gt_i32_e64 s[50:51], v43, v143
	v_addc_co_u32_e64 v157, s[42:43], 0, v157, s[74:75]
	v_cmp_gt_i32_e64 s[72:73], v43, v152
	v_addc_co_u32_e64 v158, s[42:43], 0, v158, s[76:77]
	v_cmp_gt_i32_e64 s[74:75], v43, v153
	v_addc_co_u32_e64 v159, s[42:43], 0, v159, s[50:51]
	v_cmp_gt_i32_e64 s[76:77], v43, v154
	v_addc_co_u32_e64 v160, s[42:43], 0, v160, s[72:73]
	v_cmp_gt_i32_e64 s[50:51], v43, v155
	v_addc_co_u32_e64 v161, s[42:43], 0, v161, s[74:75]
	v_cmp_gt_i32_e64 s[72:73], v44, v140
	v_addc_co_u32_e64 v162, s[42:43], 0, v162, s[76:77]
	v_cmp_gt_i32_e64 s[74:75], v44, v141
	v_addc_co_u32_e64 v163, s[42:43], 0, v163, s[50:51]
	v_cmp_gt_i32_e64 s[76:77], v44, v142
	v_addc_co_u32_e64 v156, s[42:43], 0, v156, s[72:73]
	v_cmp_gt_i32_e64 s[50:51], v44, v143
	v_addc_co_u32_e64 v157, s[42:43], 0, v157, s[74:75]
	v_cmp_gt_i32_e64 s[72:73], v44, v144
	v_addc_co_u32_e64 v158, s[42:43], 0, v158, s[76:77]
	v_cmp_gt_i32_e64 s[74:75], v44, v153
	v_addc_co_u32_e64 v159, s[42:43], 0, v159, s[50:51]
	v_cmp_gt_i32_e64 s[76:77], v44, v154
	v_addc_co_u32_e64 v160, s[42:43], 0, v160, s[72:73]
	v_cmp_gt_i32_e64 s[50:51], v44, v155
	v_addc_co_u32_e64 v161, s[42:43], 0, v161, s[74:75]
	v_cmp_gt_i32_e64 s[72:73], v45, v140
	v_addc_co_u32_e64 v162, s[42:43], 0, v162, s[76:77]
	v_cmp_gt_i32_e64 s[74:75], v45, v141
	v_addc_co_u32_e64 v163, s[42:43], 0, v163, s[50:51]
	v_cmp_gt_i32_e64 s[76:77], v45, v142
	v_addc_co_u32_e64 v156, s[42:43], 0, v156, s[72:73]
	v_cmp_gt_i32_e64 s[50:51], v45, v143
	v_addc_co_u32_e64 v157, s[42:43], 0, v157, s[74:75]
	v_cmp_gt_i32_e64 s[72:73], v45, v144
	v_addc_co_u32_e64 v158, s[42:43], 0, v158, s[76:77]
	v_cmp_gt_i32_e64 s[74:75], v45, v145
	v_addc_co_u32_e64 v159, s[42:43], 0, v159, s[50:51]
	v_cmp_gt_i32_e64 s[76:77], v45, v154
	v_addc_co_u32_e64 v160, s[42:43], 0, v160, s[72:73]
	v_cmp_gt_i32_e64 s[50:51], v45, v155
	v_addc_co_u32_e64 v161, s[42:43], 0, v161, s[74:75]
	v_cmp_gt_i32_e64 s[72:73], v46, v140
	v_addc_co_u32_e64 v162, s[42:43], 0, v162, s[76:77]
	v_cmp_gt_i32_e64 s[74:75], v46, v141
	v_addc_co_u32_e64 v163, s[42:43], 0, v163, s[50:51]
	v_cmp_gt_i32_e64 s[76:77], v46, v142
	v_addc_co_u32_e64 v156, s[42:43], 0, v156, s[72:73]
	v_cmp_gt_i32_e64 s[50:51], v46, v143
	v_addc_co_u32_e64 v157, s[42:43], 0, v157, s[74:75]
	v_cmp_gt_i32_e64 s[72:73], v46, v144
	v_addc_co_u32_e64 v158, s[42:43], 0, v158, s[76:77]
	v_cmp_gt_i32_e64 s[74:75], v46, v145
	v_addc_co_u32_e64 v159, s[42:43], 0, v159, s[50:51]
	v_cmp_gt_i32_e64 s[76:77], v46, v146
	v_addc_co_u32_e64 v160, s[42:43], 0, v160, s[72:73]
	v_cmp_gt_i32_e64 s[50:51], v46, v155
	v_addc_co_u32_e64 v161, s[42:43], 0, v161, s[74:75]
	v_cmp_gt_i32_e64 s[72:73], v47, v140
	v_addc_co_u32_e64 v162, s[42:43], 0, v162, s[76:77]
	v_cmp_gt_i32_e64 s[74:75], v47, v141
	v_addc_co_u32_e64 v163, s[42:43], 0, v163, s[50:51]
	v_cmp_gt_i32_e64 s[76:77], v47, v142
	v_addc_co_u32_e64 v156, s[42:43], 0, v156, s[72:73]
	v_cmp_gt_i32_e64 s[50:51], v47, v143
	v_addc_co_u32_e64 v157, s[42:43], 0, v157, s[74:75]
	v_cmp_gt_i32_e64 s[72:73], v47, v144
	v_addc_co_u32_e64 v158, s[42:43], 0, v158, s[76:77]
	v_cmp_gt_i32_e64 s[74:75], v47, v145
	v_addc_co_u32_e64 v159, s[42:43], 0, v159, s[50:51]
	v_cmp_gt_i32_e64 s[76:77], v47, v146
	v_addc_co_u32_e64 v160, s[42:43], 0, v160, s[72:73]
	v_cmp_gt_i32_e64 s[50:51], v47, v147
	v_addc_co_u32_e64 v161, s[42:43], 0, v161, s[74:75]
	v_addc_co_u32_e64 v162, s[42:43], 0, v162, s[76:77]
	v_addc_co_u32_e64 v163, s[42:43], 0, v163, s[50:51]
	s_cmp_gt_u32 32, s9
	s_cbranch_scc1 .Ltopk_oct_done
; DI void task_nsa(const P& p, int layer, int task, bf16_t* sm, int dm) {
;     ...
;     int rank = 0;
; #pragma unroll 4
;     for (int jp = 0; jp < 64; ++jp) {
;       const float sj = __int_as_float(__builtin_amdgcn_readlane(__float_as_int(score), jp));
;       rank += ((sj > score) || (sj == score && jp < j)) ? 1 : 0;
;     }
	ds_read_b32 v56, v171 offset:49568
	ds_read_b32 v57, v171 offset:49828
	ds_read_b32 v58, v171 offset:50088
	ds_read_b32 v59, v171 offset:50348
	ds_read_b32 v60, v171 offset:50608
	ds_read_b32 v61, v171 offset:50868
	ds_read_b32 v62, v171 offset:51128
	ds_read_b32 v63, v171 offset:51388
	s_cmp_lt_u32 4, s28
	s_cselect_b32 s31, 1, 0
	s_cmp_le_u32 4, s28
	s_cselect_b32 s32, 1, 0
	v_subrev_u32_e32 v140, s31, v116
	v_subrev_u32_e32 v141, s31, v117
	v_subrev_u32_e32 v142, s31, v118
	v_subrev_u32_e32 v143, s31, v119
	v_subrev_u32_e32 v144, s31, v120
	v_subrev_u32_e32 v145, s31, v121
	v_subrev_u32_e32 v146, s31, v122
	v_subrev_u32_e32 v147, s31, v123
	v_subrev_u32_e32 v148, s32, v116
	v_subrev_u32_e32 v149, s32, v117
	v_subrev_u32_e32 v150, s32, v118
	v_subrev_u32_e32 v151, s32, v119
	v_subrev_u32_e32 v152, s32, v120
	v_subrev_u32_e32 v153, s32, v121
	v_subrev_u32_e32 v154, s32, v122
	v_subrev_u32_e32 v155, s32, v123
	s_waitcnt lgkmcnt(8)
	v_cmp_gt_i32_e64 s[72:73], v48, v140
	v_cmp_gt_i32_e64 s[74:75], v48, v149
	v_cmp_gt_i32_e64 s[76:77], v48, v150
	v_addc_co_u32_e64 v156, s[42:43], 0, v156, s[72:73]
	v_cmp_gt_i32_e64 s[50:51], v48, v151
	v_addc_co_u32_e64 v157, s[42:43], 0, v157, s[74:75]
	v_cmp_gt_i32_e64 s[72:73], v48, v152
	v_addc_co_u32_e64 v158, s[42:43], 0, v158, s[76:77]
	v_cmp_gt_i32_e64 s[74:75], v48, v153
	v_addc_co_u32_e64 v159, s[42:43], 0, v159, s[50:51]
	v_cmp_gt_i32_e64 s[76:77], v48, v154
	v_addc_co_u32_e64 v160, s[42:43], 0, v160, s[72:73]
	v_cmp_gt_i32_e64 s[50:51], v48, v155
	v_addc_co_u32_e64 v161, s[42:43], 0, v161, s[74:75]
	v_cmp_gt_i32_e64 s[72:73], v49, v140
	v_addc_co_u32_e64 v162, s[42:43], 0, v162, s[76:77]
	v_cmp_gt_i32_e64 s[74:75], v49, v141
	v_addc_co_u32_e64 v163, s[42:43], 0, v163, s[50:51]
	v_cmp_gt_i32_e64 s[76:77], v49, v150
	v_addc_co_u32_e64 v156, s[42:43], 0, v156, s[72:73]
	v_cmp_gt_i32_e64 s[50:51], v49, v151
	v_addc_co_u32_e64 v157, s[42:43], 0, v157, s[74:75]
	v_cmp_gt_i32_e64 s[72:73], v49, v152
	v_addc_co_u32_e64 v158, s[42:43], 0, v158, s[76:77]
	v_cmp_gt_i32_e64 s[74:75], v49, v153
	v_addc_co_u32_e64 v159, s[42:43], 0, v159, s[50:51]
	v_cmp_gt_i32_e64 s[76:77], v49, v154
	v_addc_co_u32_e64 v160, s[42:43], 0, v160, s[72:73]
	v_cmp_gt_i32_e64 s[50:51], v49, v155
	v_addc_co_u32_e64 v161, s[42:43], 0, v161, s[74:75]
	v_cmp_gt_i32_e64 s[72:73], v50, v140
	v_addc_co_u32_e64 v162, s[42:43], 0, v162, s[76:77]
	v_cmp_gt_i32_e64 s[74:75], v50, v141
	v_addc_co_u32_e64 v163, s[42:43], 0, v163, s[50:51]
	v_cmp_gt_i32_e64 s[76:77], v50, v142
	v_addc_co_u32_e64 v156, s[42:43], 0, v156, s[72:73]
	v_cmp_gt_i32_e64 s[50:51], v50, v151
	v_addc_co_u32_e64 v157, s[42:43], 0, v157, s[74:75]
	v_cmp_gt_i32_e64 s[72:73], v50, v152
	v_addc_co_u32_e64 v158, s[42:43], 0, v158, s[76:77]
	v_cmp_gt_i32_e64 s[74:75], v50, v153
	v_addc_co_u32_e64 v159, s[42:43], 0, v159, s[50:51]
	v_cmp_gt_i32_e64 s[76:77], v50, v154
	v_addc_co_u32_e64 v160, s[42:43], 0, v160, s[72:73]
	v_cmp_gt_i32_e64 s[50:51], v50, v155
	v_addc_co_u32_e64 v161, s[42:43], 0, v161, s[74:75]
	v_cmp_gt_i32_e64 s[72:73], v51, v140
	v_addc_co_u32_e64 v162, s[42:43], 0, v162, s[76:77]
	v_cmp_gt_i32_e64 s[74:75], v51, v141
	v_addc_co_u32_e64 v163, s[42:43], 0, v163, s[50:51]
	v_cmp_gt_i32_e64 s[76:77], v51, v142
	v_addc_co_u32_e64 v156, s[42:43], 0, v156, s[72:73]
	v_cmp_gt_i32_e64 s[50:51], v51, v143
	v_addc_co_u32_e64 v157, s[42:43], 0, v157, s[74:75]
	v_cmp_gt_i32_e64 s[72:73], v51, v152
	v_addc_co_u32_e64 v158, s[42:43], 0, v158, s[76:77]
	v_cmp_gt_i32_e64 s[74:75], v51, v153
	v_addc_co_u32_e64 v159, s[42:43], 0, v159, s[50:51]
	v_cmp_gt_i32_e64 s[76:77], v51, v154
	v_addc_co_u32_e64 v160, s[42:43], 0, v160, s[72:73]
	v_cmp_gt_i32_e64 s[50:51], v51, v155
	v_addc_co_u32_e64 v161, s[42:43], 0, v161, s[74:75]
	v_cmp_gt_i32_e64 s[72:73], v52, v140
	v_addc_co_u32_e64 v162, s[42:43], 0, v162, s[76:77]
	v_cmp_gt_i32_e64 s[74:75], v52, v141
	v_addc_co_u32_e64 v163, s[42:43], 0, v163, s[50:51]
	v_cmp_gt_i32_e64 s[76:77], v52, v142
	v_addc_co_u32_e64 v156, s[42:43], 0, v156, s[72:73]
	v_cmp_gt_i32_e64 s[50:51], v52, v143
	v_addc_co_u32_e64 v157, s[42:43], 0, v157, s[74:75]
	v_cmp_gt_i32_e64 s[72:73], v52, v144
	v_addc_co_u32_e64 v158, s[42:43], 0, v158, s[76:77]
	v_cmp_gt_i32_e64 s[74:75], v52, v153
	v_addc_co_u32_e64 v159, s[42:43], 0, v159, s[50:51]
	v_cmp_gt_i32_e64 s[76:77], v52, v154
	v_addc_co_u32_e64 v160, s[42:43], 0, v160, s[72:73]
	v_cmp_gt_i32_e64 s[50:51], v52, v155
	v_addc_co_u32_e64 v161, s[42:43], 0, v161, s[74:75]
	v_cmp_gt_i32_e64 s[72:73], v53, v140
	v_addc_co_u32_e64 v162, s[42:43], 0, v162, s[76:77]
	v_cmp_gt_i32_e64 s[74:75], v53, v141
	v_addc_co_u32_e64 v163, s[42:43], 0, v163, s[50:51]
	v_cmp_gt_i32_e64 s[76:77], v53, v142
	v_addc_co_u32_e64 v156, s[42:43], 0, v156, s[72:73]
	v_cmp_gt_i32_e64 s[50:51], v53, v143
	v_addc_co_u32_e64 v157, s[42:43], 0, v157, s[74:75]
	v_cmp_gt_i32_e64 s[72:73], v53, v144
	v_addc_co_u32_e64 v158, s[42:43], 0, v158, s[76:77]
	v_cmp_gt_i32_e64 s[74:75], v53, v145
	v_addc_co_u32_e64 v159, s[42:43], 0, v159, s[50:51]
	v_cmp_gt_i32_e64 s[76:77], v53, v154
	v_addc_co_u32_e64 v160, s[42:43], 0, v160, s[72:73]
	v_cmp_gt_i32_e64 s[50:51], v53, v155
	v_addc_co_u32_e64 v161, s[42:43], 0, v161, s[74:75]
	v_cmp_gt_i32_e64 s[72:73], v54, v140
	v_addc_co_u32_e64 v162, s[42:43], 0, v162, s[76:77]
	v_cmp_gt_i32_e64 s[74:75], v54, v141
	v_addc_co_u32_e64 v163, s[42:43], 0, v163, s[50:51]
	v_cmp_gt_i32_e64 s[76:77], v54, v142
	v_addc_co_u32_e64 v156, s[42:43], 0, v156, s[72:73]
	v_cmp_gt_i32_e64 s[50:51], v54, v143
	v_addc_co_u32_e64 v157, s[42:43], 0, v157, s[74:75]
	v_cmp_gt_i32_e64 s[72:73], v54, v144
	v_addc_co_u32_e64 v158, s[42:43], 0, v158, s[76:77]
	v_cmp_gt_i32_e64 s[74:75], v54, v145
	v_addc_co_u32_e64 v159, s[42:43], 0, v159, s[50:51]
	v_cmp_gt_i32_e64 s[76:77], v54, v146
	v_addc_co_u32_e64 v160, s[42:43], 0, v160, s[72:73]
	v_cmp_gt_i32_e64 s[50:51], v54, v155
	v_addc_co_u32_e64 v161, s[42:43], 0, v161, s[74:75]
	v_cmp_gt_i32_e64 s[72:73], v55, v140
	v_addc_co_u32_e64 v162, s[42:43], 0, v162, s[76:77]
	v_cmp_gt_i32_e64 s[74:75], v55, v141
	v_addc_co_u32_e64 v163, s[42:43], 0, v163, s[50:51]
	v_cmp_gt_i32_e64 s[76:77], v55, v142
	v_addc_co_u32_e64 v156, s[42:43], 0, v156, s[72:73]
	v_cmp_gt_i32_e64 s[50:51], v55, v143
	v_addc_co_u32_e64 v157, s[42:43], 0, v157, s[74:75]
	v_cmp_gt_i32_e64 s[72:73], v55, v144
	v_addc_co_u32_e64 v158, s[42:43], 0, v158, s[76:77]
	v_cmp_gt_i32_e64 s[74:75], v55, v145
	v_addc_co_u32_e64 v159, s[42:43], 0, v159, s[50:51]
	v_cmp_gt_i32_e64 s[76:77], v55, v146
	v_addc_co_u32_e64 v160, s[42:43], 0, v160, s[72:73]
	v_cmp_gt_i32_e64 s[50:51], v55, v147
	v_addc_co_u32_e64 v161, s[42:43], 0, v161, s[74:75]
	v_addc_co_u32_e64 v162, s[42:43], 0, v162, s[76:77]
	v_addc_co_u32_e64 v163, s[42:43], 0, v163, s[50:51]
	s_cmp_gt_u32 40, s9
	s_cbranch_scc1 .Ltopk_oct_done
; DI void task_nsa(const P& p, int layer, int task, bf16_t* sm, int dm) {
;     ...
;     int rank = 0;
; #pragma unroll 4
;     for (int jp = 0; jp < 64; ++jp) {
;       const float sj = __int_as_float(__builtin_amdgcn_readlane(__float_as_int(score), jp));
;       rank += ((sj > score) || (sj == score && jp < j)) ? 1 : 0;
;     }
	ds_read_b32 v100, v171 offset:51648
	ds_read_b32 v101, v171 offset:51908
	ds_read_b32 v102, v171 offset:52168
	ds_read_b32 v103, v171 offset:52428
	ds_read_b32 v104, v171 offset:52688
	ds_read_b32 v105, v171 offset:52948
	ds_read_b32 v106, v171 offset:53208
	ds_read_b32 v107, v171 offset:53468
	s_cmp_lt_u32 5, s28
	s_cselect_b32 s31, 1, 0
	s_cmp_le_u32 5, s28
	s_cselect_b32 s32, 1, 0
	v_subrev_u32_e32 v140, s31, v116
	v_subrev_u32_e32 v141, s31, v117
	v_subrev_u32_e32 v142, s31, v118
	v_subrev_u32_e32 v143, s31, v119
	v_subrev_u32_e32 v144, s31, v120
	v_subrev_u32_e32 v145, s31, v121
	v_subrev_u32_e32 v146, s31, v122
	v_subrev_u32_e32 v147, s31, v123
	v_subrev_u32_e32 v148, s32, v116
	v_subrev_u32_e32 v149, s32, v117
	v_subrev_u32_e32 v150, s32, v118
	v_subrev_u32_e32 v151, s32, v119
	v_subrev_u32_e32 v152, s32, v120
	v_subrev_u32_e32 v153, s32, v121
	v_subrev_u32_e32 v154, s32, v122
	v_subrev_u32_e32 v155, s32, v123
	s_waitcnt lgkmcnt(8)
	v_cmp_gt_i32_e64 s[72:73], v56, v140
	v_cmp_gt_i32_e64 s[74:75], v56, v149
	v_cmp_gt_i32_e64 s[76:77], v56, v150
	v_addc_co_u32_e64 v156, s[42:43], 0, v156, s[72:73]
	v_cmp_gt_i32_e64 s[50:51], v56, v151
	v_addc_co_u32_e64 v157, s[42:43], 0, v157, s[74:75]
	v_cmp_gt_i32_e64 s[72:73], v56, v152
	v_addc_co_u32_e64 v158, s[42:43], 0, v158, s[76:77]
	v_cmp_gt_i32_e64 s[74:75], v56, v153
	v_addc_co_u32_e64 v159, s[42:43], 0, v159, s[50:51]
	v_cmp_gt_i32_e64 s[76:77], v56, v154
	v_addc_co_u32_e64 v160, s[42:43], 0, v160, s[72:73]
	v_cmp_gt_i32_e64 s[50:51], v56, v155
	v_addc_co_u32_e64 v161, s[42:43], 0, v161, s[74:75]
	v_cmp_gt_i32_e64 s[72:73], v57, v140
	v_addc_co_u32_e64 v162, s[42:43], 0, v162, s[76:77]
	v_cmp_gt_i32_e64 s[74:75], v57, v141
	v_addc_co_u32_e64 v163, s[42:43], 0, v163, s[50:51]
	v_cmp_gt_i32_e64 s[76:77], v57, v150
	v_addc_co_u32_e64 v156, s[42:43], 0, v156, s[72:73]
	v_cmp_gt_i32_e64 s[50:51], v57, v151
	v_addc_co_u32_e64 v157, s[42:43], 0, v157, s[74:75]
	v_cmp_gt_i32_e64 s[72:73], v57, v152
	v_addc_co_u32_e64 v158, s[42:43], 0, v158, s[76:77]
	v_cmp_gt_i32_e64 s[74:75], v57, v153
	v_addc_co_u32_e64 v159, s[42:43], 0, v159, s[50:51]
	v_cmp_gt_i32_e64 s[76:77], v57, v154
	v_addc_co_u32_e64 v160, s[42:43], 0, v160, s[72:73]
	v_cmp_gt_i32_e64 s[50:51], v57, v155
	v_addc_co_u32_e64 v161, s[42:43], 0, v161, s[74:75]
	v_cmp_gt_i32_e64 s[72:73], v58, v140
	v_addc_co_u32_e64 v162, s[42:43], 0, v162, s[76:77]
	v_cmp_gt_i32_e64 s[74:75], v58, v141
	v_addc_co_u32_e64 v163, s[42:43], 0, v163, s[50:51]
	v_cmp_gt_i32_e64 s[76:77], v58, v142
	v_addc_co_u32_e64 v156, s[42:43], 0, v156, s[72:73]
	v_cmp_gt_i32_e64 s[50:51], v58, v151
	v_addc_co_u32_e64 v157, s[42:43], 0, v157, s[74:75]
	v_cmp_gt_i32_e64 s[72:73], v58, v152
	v_addc_co_u32_e64 v158, s[42:43], 0, v158, s[76:77]
	v_cmp_gt_i32_e64 s[74:75], v58, v153
	v_addc_co_u32_e64 v159, s[42:43], 0, v159, s[50:51]
	v_cmp_gt_i32_e64 s[76:77], v58, v154
	v_addc_co_u32_e64 v160, s[42:43], 0, v160, s[72:73]
	v_cmp_gt_i32_e64 s[50:51], v58, v155
	v_addc_co_u32_e64 v161, s[42:43], 0, v161, s[74:75]
	v_cmp_gt_i32_e64 s[72:73], v59, v140
	v_addc_co_u32_e64 v162, s[42:43], 0, v162, s[76:77]
	v_cmp_gt_i32_e64 s[74:75], v59, v141
	v_addc_co_u32_e64 v163, s[42:43], 0, v163, s[50:51]
	v_cmp_gt_i32_e64 s[76:77], v59, v142
	v_addc_co_u32_e64 v156, s[42:43], 0, v156, s[72:73]
	v_cmp_gt_i32_e64 s[50:51], v59, v143
	v_addc_co_u32_e64 v157, s[42:43], 0, v157, s[74:75]
	v_cmp_gt_i32_e64 s[72:73], v59, v152
	v_addc_co_u32_e64 v158, s[42:43], 0, v158, s[76:77]
	v_cmp_gt_i32_e64 s[74:75], v59, v153
	v_addc_co_u32_e64 v159, s[42:43], 0, v159, s[50:51]
	v_cmp_gt_i32_e64 s[76:77], v59, v154
	v_addc_co_u32_e64 v160, s[42:43], 0, v160, s[72:73]
	v_cmp_gt_i32_e64 s[50:51], v59, v155
	v_addc_co_u32_e64 v161, s[42:43], 0, v161, s[74:75]
	v_cmp_gt_i32_e64 s[72:73], v60, v140
	v_addc_co_u32_e64 v162, s[42:43], 0, v162, s[76:77]
	v_cmp_gt_i32_e64 s[74:75], v60, v141
	v_addc_co_u32_e64 v163, s[42:43], 0, v163, s[50:51]
	v_cmp_gt_i32_e64 s[76:77], v60, v142
	v_addc_co_u32_e64 v156, s[42:43], 0, v156, s[72:73]
	v_cmp_gt_i32_e64 s[50:51], v60, v143
	v_addc_co_u32_e64 v157, s[42:43], 0, v157, s[74:75]
	v_cmp_gt_i32_e64 s[72:73], v60, v144
	v_addc_co_u32_e64 v158, s[42:43], 0, v158, s[76:77]
	v_cmp_gt_i32_e64 s[74:75], v60, v153
	v_addc_co_u32_e64 v159, s[42:43], 0, v159, s[50:51]
	v_cmp_gt_i32_e64 s[76:77], v60, v154
	v_addc_co_u32_e64 v160, s[42:43], 0, v160, s[72:73]
	v_cmp_gt_i32_e64 s[50:51], v60, v155
	v_addc_co_u32_e64 v161, s[42:43], 0, v161, s[74:75]
	v_cmp_gt_i32_e64 s[72:73], v61, v140
	v_addc_co_u32_e64 v162, s[42:43], 0, v162, s[76:77]
	v_cmp_gt_i32_e64 s[74:75], v61, v141
	v_addc_co_u32_e64 v163, s[42:43], 0, v163, s[50:51]
	v_cmp_gt_i32_e64 s[76:77], v61, v142
	v_addc_co_u32_e64 v156, s[42:43], 0, v156, s[72:73]
	v_cmp_gt_i32_e64 s[50:51], v61, v143
	v_addc_co_u32_e64 v157, s[42:43], 0, v157, s[74:75]
	v_cmp_gt_i32_e64 s[72:73], v61, v144
	v_addc_co_u32_e64 v158, s[42:43], 0, v158, s[76:77]
	v_cmp_gt_i32_e64 s[74:75], v61, v145
	v_addc_co_u32_e64 v159, s[42:43], 0, v159, s[50:51]
	v_cmp_gt_i32_e64 s[76:77], v61, v154
	v_addc_co_u32_e64 v160, s[42:43], 0, v160, s[72:73]
	v_cmp_gt_i32_e64 s[50:51], v61, v155
	v_addc_co_u32_e64 v161, s[42:43], 0, v161, s[74:75]
	v_cmp_gt_i32_e64 s[72:73], v62, v140
	v_addc_co_u32_e64 v162, s[42:43], 0, v162, s[76:77]
	v_cmp_gt_i32_e64 s[74:75], v62, v141
	v_addc_co_u32_e64 v163, s[42:43], 0, v163, s[50:51]
	v_cmp_gt_i32_e64 s[76:77], v62, v142
	v_addc_co_u32_e64 v156, s[42:43], 0, v156, s[72:73]
	v_cmp_gt_i32_e64 s[50:51], v62, v143
	v_addc_co_u32_e64 v157, s[42:43], 0, v157, s[74:75]
	v_cmp_gt_i32_e64 s[72:73], v62, v144
	v_addc_co_u32_e64 v158, s[42:43], 0, v158, s[76:77]
	v_cmp_gt_i32_e64 s[74:75], v62, v145
	v_addc_co_u32_e64 v159, s[42:43], 0, v159, s[50:51]
	v_cmp_gt_i32_e64 s[76:77], v62, v146
	v_addc_co_u32_e64 v160, s[42:43], 0, v160, s[72:73]
	v_cmp_gt_i32_e64 s[50:51], v62, v155
	v_addc_co_u32_e64 v161, s[42:43], 0, v161, s[74:75]
	v_cmp_gt_i32_e64 s[72:73], v63, v140
	v_addc_co_u32_e64 v162, s[42:43], 0, v162, s[76:77]
	v_cmp_gt_i32_e64 s[74:75], v63, v141
	v_addc_co_u32_e64 v163, s[42:43], 0, v163, s[50:51]
	v_cmp_gt_i32_e64 s[76:77], v63, v142
	v_addc_co_u32_e64 v156, s[42:43], 0, v156, s[72:73]
	v_cmp_gt_i32_e64 s[50:51], v63, v143
	v_addc_co_u32_e64 v157, s[42:43], 0, v157, s[74:75]
	v_cmp_gt_i32_e64 s[72:73], v63, v144
	v_addc_co_u32_e64 v158, s[42:43], 0, v158, s[76:77]
	v_cmp_gt_i32_e64 s[74:75], v63, v145
	v_addc_co_u32_e64 v159, s[42:43], 0, v159, s[50:51]
	v_cmp_gt_i32_e64 s[76:77], v63, v146
	v_addc_co_u32_e64 v160, s[42:43], 0, v160, s[72:73]
	v_cmp_gt_i32_e64 s[50:51], v63, v147
	v_addc_co_u32_e64 v161, s[42:43], 0, v161, s[74:75]
	v_addc_co_u32_e64 v162, s[42:43], 0, v162, s[76:77]
	v_addc_co_u32_e64 v163, s[42:43], 0, v163, s[50:51]
	s_cmp_gt_u32 48, s9
	s_cbranch_scc1 .Ltopk_oct_done
; DI void task_nsa(const P& p, int layer, int task, bf16_t* sm, int dm) {
;     ...
;     int rank = 0;
; #pragma unroll 4
;     for (int jp = 0; jp < 64; ++jp) {
;       const float sj = __int_as_float(__builtin_amdgcn_readlane(__float_as_int(score), jp));
;       rank += ((sj > score) || (sj == score && jp < j)) ? 1 : 0;
;     }
	ds_read_b32 v108, v171 offset:53728
	ds_read_b32 v109, v171 offset:53988
	ds_read_b32 v110, v171 offset:54248
	ds_read_b32 v111, v171 offset:54508
	ds_read_b32 v112, v171 offset:54768
	ds_read_b32 v113, v171 offset:55028
	ds_read_b32 v114, v171 offset:55288
	ds_read_b32 v115, v171 offset:55548
	s_cmp_lt_u32 6, s28
	s_cselect_b32 s31, 1, 0
	s_cmp_le_u32 6, s28
	s_cselect_b32 s32, 1, 0
	v_subrev_u32_e32 v140, s31, v116
	v_subrev_u32_e32 v141, s31, v117
	v_subrev_u32_e32 v142, s31, v118
	v_subrev_u32_e32 v143, s31, v119
	v_subrev_u32_e32 v144, s31, v120
	v_subrev_u32_e32 v145, s31, v121
	v_subrev_u32_e32 v146, s31, v122
	v_subrev_u32_e32 v147, s31, v123
	v_subrev_u32_e32 v148, s32, v116
	v_subrev_u32_e32 v149, s32, v117
	v_subrev_u32_e32 v150, s32, v118
	v_subrev_u32_e32 v151, s32, v119
	v_subrev_u32_e32 v152, s32, v120
	v_subrev_u32_e32 v153, s32, v121
	v_subrev_u32_e32 v154, s32, v122
	v_subrev_u32_e32 v155, s32, v123
	s_waitcnt lgkmcnt(8)
	v_cmp_gt_i32_e64 s[72:73], v100, v140
	v_cmp_gt_i32_e64 s[74:75], v100, v149
	v_cmp_gt_i32_e64 s[76:77], v100, v150
	v_addc_co_u32_e64 v156, s[42:43], 0, v156, s[72:73]
	v_cmp_gt_i32_e64 s[50:51], v100, v151
	v_addc_co_u32_e64 v157, s[42:43], 0, v157, s[74:75]
	v_cmp_gt_i32_e64 s[72:73], v100, v152
	v_addc_co_u32_e64 v158, s[42:43], 0, v158, s[76:77]
	v_cmp_gt_i32_e64 s[74:75], v100, v153
	v_addc_co_u32_e64 v159, s[42:43], 0, v159, s[50:51]
	v_cmp_gt_i32_e64 s[76:77], v100, v154
	v_addc_co_u32_e64 v160, s[42:43], 0, v160, s[72:73]
	v_cmp_gt_i32_e64 s[50:51], v100, v155
	v_addc_co_u32_e64 v161, s[42:43], 0, v161, s[74:75]
	v_cmp_gt_i32_e64 s[72:73], v101, v140
	v_addc_co_u32_e64 v162, s[42:43], 0, v162, s[76:77]
	v_cmp_gt_i32_e64 s[74:75], v101, v141
	v_addc_co_u32_e64 v163, s[42:43], 0, v163, s[50:51]
	v_cmp_gt_i32_e64 s[76:77], v101, v150
	v_addc_co_u32_e64 v156, s[42:43], 0, v156, s[72:73]
	v_cmp_gt_i32_e64 s[50:51], v101, v151
	v_addc_co_u32_e64 v157, s[42:43], 0, v157, s[74:75]
	v_cmp_gt_i32_e64 s[72:73], v101, v152
	v_addc_co_u32_e64 v158, s[42:43], 0, v158, s[76:77]
	v_cmp_gt_i32_e64 s[74:75], v101, v153
	v_addc_co_u32_e64 v159, s[42:43], 0, v159, s[50:51]
	v_cmp_gt_i32_e64 s[76:77], v101, v154
	v_addc_co_u32_e64 v160, s[42:43], 0, v160, s[72:73]
	v_cmp_gt_i32_e64 s[50:51], v101, v155
	v_addc_co_u32_e64 v161, s[42:43], 0, v161, s[74:75]
	v_cmp_gt_i32_e64 s[72:73], v102, v140
	v_addc_co_u32_e64 v162, s[42:43], 0, v162, s[76:77]
	v_cmp_gt_i32_e64 s[74:75], v102, v141
	v_addc_co_u32_e64 v163, s[42:43], 0, v163, s[50:51]
	v_cmp_gt_i32_e64 s[76:77], v102, v142
	v_addc_co_u32_e64 v156, s[42:43], 0, v156, s[72:73]
	v_cmp_gt_i32_e64 s[50:51], v102, v151
	v_addc_co_u32_e64 v157, s[42:43], 0, v157, s[74:75]
	v_cmp_gt_i32_e64 s[72:73], v102, v152
	v_addc_co_u32_e64 v158, s[42:43], 0, v158, s[76:77]
	v_cmp_gt_i32_e64 s[74:75], v102, v153
	v_addc_co_u32_e64 v159, s[42:43], 0, v159, s[50:51]
	v_cmp_gt_i32_e64 s[76:77], v102, v154
	v_addc_co_u32_e64 v160, s[42:43], 0, v160, s[72:73]
	v_cmp_gt_i32_e64 s[50:51], v102, v155
	v_addc_co_u32_e64 v161, s[42:43], 0, v161, s[74:75]
	v_cmp_gt_i32_e64 s[72:73], v103, v140
	v_addc_co_u32_e64 v162, s[42:43], 0, v162, s[76:77]
	v_cmp_gt_i32_e64 s[74:75], v103, v141
	v_addc_co_u32_e64 v163, s[42:43], 0, v163, s[50:51]
	v_cmp_gt_i32_e64 s[76:77], v103, v142
	v_addc_co_u32_e64 v156, s[42:43], 0, v156, s[72:73]
	v_cmp_gt_i32_e64 s[50:51], v103, v143
	v_addc_co_u32_e64 v157, s[42:43], 0, v157, s[74:75]
	v_cmp_gt_i32_e64 s[72:73], v103, v152
	v_addc_co_u32_e64 v158, s[42:43], 0, v158, s[76:77]
	v_cmp_gt_i32_e64 s[74:75], v103, v153
	v_addc_co_u32_e64 v159, s[42:43], 0, v159, s[50:51]
	v_cmp_gt_i32_e64 s[76:77], v103, v154
	v_addc_co_u32_e64 v160, s[42:43], 0, v160, s[72:73]
	v_cmp_gt_i32_e64 s[50:51], v103, v155
	v_addc_co_u32_e64 v161, s[42:43], 0, v161, s[74:75]
	v_cmp_gt_i32_e64 s[72:73], v104, v140
	v_addc_co_u32_e64 v162, s[42:43], 0, v162, s[76:77]
	v_cmp_gt_i32_e64 s[74:75], v104, v141
	v_addc_co_u32_e64 v163, s[42:43], 0, v163, s[50:51]
	v_cmp_gt_i32_e64 s[76:77], v104, v142
	v_addc_co_u32_e64 v156, s[42:43], 0, v156, s[72:73]
	v_cmp_gt_i32_e64 s[50:51], v104, v143
	v_addc_co_u32_e64 v157, s[42:43], 0, v157, s[74:75]
	v_cmp_gt_i32_e64 s[72:73], v104, v144
	v_addc_co_u32_e64 v158, s[42:43], 0, v158, s[76:77]
	v_cmp_gt_i32_e64 s[74:75], v104, v153
	v_addc_co_u32_e64 v159, s[42:43], 0, v159, s[50:51]
	v_cmp_gt_i32_e64 s[76:77], v104, v154
	v_addc_co_u32_e64 v160, s[42:43], 0, v160, s[72:73]
	v_cmp_gt_i32_e64 s[50:51], v104, v155
	v_addc_co_u32_e64 v161, s[42:43], 0, v161, s[74:75]
	v_cmp_gt_i32_e64 s[72:73], v105, v140
	v_addc_co_u32_e64 v162, s[42:43], 0, v162, s[76:77]
	v_cmp_gt_i32_e64 s[74:75], v105, v141
	v_addc_co_u32_e64 v163, s[42:43], 0, v163, s[50:51]
	v_cmp_gt_i32_e64 s[76:77], v105, v142
	v_addc_co_u32_e64 v156, s[42:43], 0, v156, s[72:73]
	v_cmp_gt_i32_e64 s[50:51], v105, v143
	v_addc_co_u32_e64 v157, s[42:43], 0, v157, s[74:75]
	v_cmp_gt_i32_e64 s[72:73], v105, v144
	v_addc_co_u32_e64 v158, s[42:43], 0, v158, s[76:77]
	v_cmp_gt_i32_e64 s[74:75], v105, v145
	v_addc_co_u32_e64 v159, s[42:43], 0, v159, s[50:51]
	v_cmp_gt_i32_e64 s[76:77], v105, v154
	v_addc_co_u32_e64 v160, s[42:43], 0, v160, s[72:73]
	v_cmp_gt_i32_e64 s[50:51], v105, v155
	v_addc_co_u32_e64 v161, s[42:43], 0, v161, s[74:75]
	v_cmp_gt_i32_e64 s[72:73], v106, v140
	v_addc_co_u32_e64 v162, s[42:43], 0, v162, s[76:77]
	v_cmp_gt_i32_e64 s[74:75], v106, v141
	v_addc_co_u32_e64 v163, s[42:43], 0, v163, s[50:51]
	v_cmp_gt_i32_e64 s[76:77], v106, v142
	v_addc_co_u32_e64 v156, s[42:43], 0, v156, s[72:73]
	v_cmp_gt_i32_e64 s[50:51], v106, v143
	v_addc_co_u32_e64 v157, s[42:43], 0, v157, s[74:75]
	v_cmp_gt_i32_e64 s[72:73], v106, v144
	v_addc_co_u32_e64 v158, s[42:43], 0, v158, s[76:77]
	v_cmp_gt_i32_e64 s[74:75], v106, v145
	v_addc_co_u32_e64 v159, s[42:43], 0, v159, s[50:51]
	v_cmp_gt_i32_e64 s[76:77], v106, v146
	v_addc_co_u32_e64 v160, s[42:43], 0, v160, s[72:73]
	v_cmp_gt_i32_e64 s[50:51], v106, v155
	v_addc_co_u32_e64 v161, s[42:43], 0, v161, s[74:75]
	v_cmp_gt_i32_e64 s[72:73], v107, v140
	v_addc_co_u32_e64 v162, s[42:43], 0, v162, s[76:77]
	v_cmp_gt_i32_e64 s[74:75], v107, v141
	v_addc_co_u32_e64 v163, s[42:43], 0, v163, s[50:51]
	v_cmp_gt_i32_e64 s[76:77], v107, v142
	v_addc_co_u32_e64 v156, s[42:43], 0, v156, s[72:73]
	v_cmp_gt_i32_e64 s[50:51], v107, v143
	v_addc_co_u32_e64 v157, s[42:43], 0, v157, s[74:75]
	v_cmp_gt_i32_e64 s[72:73], v107, v144
	v_addc_co_u32_e64 v158, s[42:43], 0, v158, s[76:77]
	v_cmp_gt_i32_e64 s[74:75], v107, v145
	v_addc_co_u32_e64 v159, s[42:43], 0, v159, s[50:51]
	v_cmp_gt_i32_e64 s[76:77], v107, v146
	v_addc_co_u32_e64 v160, s[42:43], 0, v160, s[72:73]
	v_cmp_gt_i32_e64 s[50:51], v107, v147
	v_addc_co_u32_e64 v161, s[42:43], 0, v161, s[74:75]
	v_addc_co_u32_e64 v162, s[42:43], 0, v162, s[76:77]
	v_addc_co_u32_e64 v163, s[42:43], 0, v163, s[50:51]
	s_cmp_gt_u32 56, s9
	s_cbranch_scc1 .Ltopk_oct_done
; DI void task_nsa(const P& p, int layer, int task, bf16_t* sm, int dm) {
;     ...
;     int rank = 0;
; #pragma unroll 4
;     for (int jp = 0; jp < 64; ++jp) {
;       const float sj = __int_as_float(__builtin_amdgcn_readlane(__float_as_int(score), jp));
;       rank += ((sj > score) || (sj == score && jp < j)) ? 1 : 0;
;     }
	s_cmp_lt_u32 7, s28
	s_cselect_b32 s31, 1, 0
	s_cmp_le_u32 7, s28
	s_cselect_b32 s32, 1, 0
	v_subrev_u32_e32 v140, s31, v116
	v_subrev_u32_e32 v141, s31, v117
	v_subrev_u32_e32 v142, s31, v118
	v_subrev_u32_e32 v143, s31, v119
	v_subrev_u32_e32 v144, s31, v120
	v_subrev_u32_e32 v145, s31, v121
	v_subrev_u32_e32 v146, s31, v122
	v_subrev_u32_e32 v147, s31, v123
	v_subrev_u32_e32 v148, s32, v116
	v_subrev_u32_e32 v149, s32, v117
	v_subrev_u32_e32 v150, s32, v118
	v_subrev_u32_e32 v151, s32, v119
	v_subrev_u32_e32 v152, s32, v120
	v_subrev_u32_e32 v153, s32, v121
	v_subrev_u32_e32 v154, s32, v122
	v_subrev_u32_e32 v155, s32, v123
	s_waitcnt lgkmcnt(0)
	v_cmp_gt_i32_e64 s[72:73], v108, v140
	v_cmp_gt_i32_e64 s[74:75], v108, v149
	v_cmp_gt_i32_e64 s[76:77], v108, v150
	v_addc_co_u32_e64 v156, s[42:43], 0, v156, s[72:73]
	v_cmp_gt_i32_e64 s[50:51], v108, v151
	v_addc_co_u32_e64 v157, s[42:43], 0, v157, s[74:75]
	v_cmp_gt_i32_e64 s[72:73], v108, v152
	v_addc_co_u32_e64 v158, s[42:43], 0, v158, s[76:77]
	v_cmp_gt_i32_e64 s[74:75], v108, v153
	v_addc_co_u32_e64 v159, s[42:43], 0, v159, s[50:51]
	v_cmp_gt_i32_e64 s[76:77], v108, v154
	v_addc_co_u32_e64 v160, s[42:43], 0, v160, s[72:73]
	v_cmp_gt_i32_e64 s[50:51], v108, v155
	v_addc_co_u32_e64 v161, s[42:43], 0, v161, s[74:75]
	v_cmp_gt_i32_e64 s[72:73], v109, v140
	v_addc_co_u32_e64 v162, s[42:43], 0, v162, s[76:77]
	v_cmp_gt_i32_e64 s[74:75], v109, v141
	v_addc_co_u32_e64 v163, s[42:43], 0, v163, s[50:51]
	v_cmp_gt_i32_e64 s[76:77], v109, v150
	v_addc_co_u32_e64 v156, s[42:43], 0, v156, s[72:73]
	v_cmp_gt_i32_e64 s[50:51], v109, v151
	v_addc_co_u32_e64 v157, s[42:43], 0, v157, s[74:75]
	v_cmp_gt_i32_e64 s[72:73], v109, v152
	v_addc_co_u32_e64 v158, s[42:43], 0, v158, s[76:77]
	v_cmp_gt_i32_e64 s[74:75], v109, v153
	v_addc_co_u32_e64 v159, s[42:43], 0, v159, s[50:51]
	v_cmp_gt_i32_e64 s[76:77], v109, v154
	v_addc_co_u32_e64 v160, s[42:43], 0, v160, s[72:73]
	v_cmp_gt_i32_e64 s[50:51], v109, v155
	v_addc_co_u32_e64 v161, s[42:43], 0, v161, s[74:75]
	v_cmp_gt_i32_e64 s[72:73], v110, v140
	v_addc_co_u32_e64 v162, s[42:43], 0, v162, s[76:77]
	v_cmp_gt_i32_e64 s[74:75], v110, v141
	v_addc_co_u32_e64 v163, s[42:43], 0, v163, s[50:51]
	v_cmp_gt_i32_e64 s[76:77], v110, v142
	v_addc_co_u32_e64 v156, s[42:43], 0, v156, s[72:73]
	v_cmp_gt_i32_e64 s[50:51], v110, v151
	v_addc_co_u32_e64 v157, s[42:43], 0, v157, s[74:75]
	v_cmp_gt_i32_e64 s[72:73], v110, v152
	v_addc_co_u32_e64 v158, s[42:43], 0, v158, s[76:77]
	v_cmp_gt_i32_e64 s[74:75], v110, v153
	v_addc_co_u32_e64 v159, s[42:43], 0, v159, s[50:51]
	v_cmp_gt_i32_e64 s[76:77], v110, v154
	v_addc_co_u32_e64 v160, s[42:43], 0, v160, s[72:73]
	v_cmp_gt_i32_e64 s[50:51], v110, v155
	v_addc_co_u32_e64 v161, s[42:43], 0, v161, s[74:75]
	v_cmp_gt_i32_e64 s[72:73], v111, v140
	v_addc_co_u32_e64 v162, s[42:43], 0, v162, s[76:77]
	v_cmp_gt_i32_e64 s[74:75], v111, v141
	v_addc_co_u32_e64 v163, s[42:43], 0, v163, s[50:51]
	v_cmp_gt_i32_e64 s[76:77], v111, v142
	v_addc_co_u32_e64 v156, s[42:43], 0, v156, s[72:73]
	v_cmp_gt_i32_e64 s[50:51], v111, v143
	v_addc_co_u32_e64 v157, s[42:43], 0, v157, s[74:75]
	v_cmp_gt_i32_e64 s[72:73], v111, v152
	v_addc_co_u32_e64 v158, s[42:43], 0, v158, s[76:77]
	v_cmp_gt_i32_e64 s[74:75], v111, v153
	v_addc_co_u32_e64 v159, s[42:43], 0, v159, s[50:51]
	v_cmp_gt_i32_e64 s[76:77], v111, v154
	v_addc_co_u32_e64 v160, s[42:43], 0, v160, s[72:73]
	v_cmp_gt_i32_e64 s[50:51], v111, v155
	v_addc_co_u32_e64 v161, s[42:43], 0, v161, s[74:75]
	v_cmp_gt_i32_e64 s[72:73], v112, v140
	v_addc_co_u32_e64 v162, s[42:43], 0, v162, s[76:77]
	v_cmp_gt_i32_e64 s[74:75], v112, v141
	v_addc_co_u32_e64 v163, s[42:43], 0, v163, s[50:51]
	v_cmp_gt_i32_e64 s[76:77], v112, v142
	v_addc_co_u32_e64 v156, s[42:43], 0, v156, s[72:73]
	v_cmp_gt_i32_e64 s[50:51], v112, v143
	v_addc_co_u32_e64 v157, s[42:43], 0, v157, s[74:75]
	v_cmp_gt_i32_e64 s[72:73], v112, v144
	v_addc_co_u32_e64 v158, s[42:43], 0, v158, s[76:77]
	v_cmp_gt_i32_e64 s[74:75], v112, v153
	v_addc_co_u32_e64 v159, s[42:43], 0, v159, s[50:51]
	v_cmp_gt_i32_e64 s[76:77], v112, v154
	v_addc_co_u32_e64 v160, s[42:43], 0, v160, s[72:73]
	v_cmp_gt_i32_e64 s[50:51], v112, v155
	v_addc_co_u32_e64 v161, s[42:43], 0, v161, s[74:75]
	v_cmp_gt_i32_e64 s[72:73], v113, v140
	v_addc_co_u32_e64 v162, s[42:43], 0, v162, s[76:77]
	v_cmp_gt_i32_e64 s[74:75], v113, v141
	v_addc_co_u32_e64 v163, s[42:43], 0, v163, s[50:51]
	v_cmp_gt_i32_e64 s[76:77], v113, v142
	v_addc_co_u32_e64 v156, s[42:43], 0, v156, s[72:73]
	v_cmp_gt_i32_e64 s[50:51], v113, v143
	v_addc_co_u32_e64 v157, s[42:43], 0, v157, s[74:75]
	v_cmp_gt_i32_e64 s[72:73], v113, v144
	v_addc_co_u32_e64 v158, s[42:43], 0, v158, s[76:77]
	v_cmp_gt_i32_e64 s[74:75], v113, v145
	v_addc_co_u32_e64 v159, s[42:43], 0, v159, s[50:51]
	v_cmp_gt_i32_e64 s[76:77], v113, v154
	v_addc_co_u32_e64 v160, s[42:43], 0, v160, s[72:73]
	v_cmp_gt_i32_e64 s[50:51], v113, v155
	v_addc_co_u32_e64 v161, s[42:43], 0, v161, s[74:75]
	v_cmp_gt_i32_e64 s[72:73], v114, v140
	v_addc_co_u32_e64 v162, s[42:43], 0, v162, s[76:77]
	v_cmp_gt_i32_e64 s[74:75], v114, v141
	v_addc_co_u32_e64 v163, s[42:43], 0, v163, s[50:51]
	v_cmp_gt_i32_e64 s[76:77], v114, v142
	v_addc_co_u32_e64 v156, s[42:43], 0, v156, s[72:73]
	v_cmp_gt_i32_e64 s[50:51], v114, v143
	v_addc_co_u32_e64 v157, s[42:43], 0, v157, s[74:75]
	v_cmp_gt_i32_e64 s[72:73], v114, v144
	v_addc_co_u32_e64 v158, s[42:43], 0, v158, s[76:77]
	v_cmp_gt_i32_e64 s[74:75], v114, v145
	v_addc_co_u32_e64 v159, s[42:43], 0, v159, s[50:51]
	v_cmp_gt_i32_e64 s[76:77], v114, v146
	v_addc_co_u32_e64 v160, s[42:43], 0, v160, s[72:73]
	v_cmp_gt_i32_e64 s[50:51], v114, v155
	v_addc_co_u32_e64 v161, s[42:43], 0, v161, s[74:75]
	v_cmp_gt_i32_e64 s[72:73], v115, v140
	v_addc_co_u32_e64 v162, s[42:43], 0, v162, s[76:77]
	v_cmp_gt_i32_e64 s[74:75], v115, v141
	v_addc_co_u32_e64 v163, s[42:43], 0, v163, s[50:51]
	v_cmp_gt_i32_e64 s[76:77], v115, v142
	v_addc_co_u32_e64 v156, s[42:43], 0, v156, s[72:73]
	v_cmp_gt_i32_e64 s[50:51], v115, v143
	v_addc_co_u32_e64 v157, s[42:43], 0, v157, s[74:75]
	v_cmp_gt_i32_e64 s[72:73], v115, v144
	v_addc_co_u32_e64 v158, s[42:43], 0, v158, s[76:77]
	v_cmp_gt_i32_e64 s[74:75], v115, v145
	v_addc_co_u32_e64 v159, s[42:43], 0, v159, s[50:51]
	v_cmp_gt_i32_e64 s[76:77], v115, v146
	v_addc_co_u32_e64 v160, s[42:43], 0, v160, s[72:73]
	v_cmp_gt_i32_e64 s[50:51], v115, v147
	v_addc_co_u32_e64 v161, s[42:43], 0, v161, s[74:75]
	v_addc_co_u32_e64 v162, s[42:43], 0, v162, s[76:77]
	v_addc_co_u32_e64 v163, s[42:43], 0, v163, s[50:51]
; DI void task_nsa(const P& p, int layer, int task, bf16_t* sm, int dm) {
;     ...
;     const unsigned long long mk = __ballot(rank < 16);
;     if (lane == 0) masks[qq] = mk;
;   }
;   __syncthreads();
;   const unsigned long long mymask = masks[ql];
;   unsigned long long un = 0ull;
;   for (int i = 0; i < 64; ++i) un |= masks[i];
;   {
;     const int cmax = qb;
;     unsigned long long todo = un & (cmax == 63 ? ~0ull : ((1ull << (cmax + 1)) - 1ull));
.Ltopk_oct_done:
	s_waitcnt lgkmcnt(0)
	v_mov_b32_e32 v164, 0
	v_cmp_gt_u32_e64 s[72:73], 16, v163
	v_cmp_gt_u32_e64 s[74:75], 16, v162
	v_cmp_gt_u32_e64 s[76:77], 16, v161
	v_addc_co_u32_e64 v164, s[42:43], v164, v164, s[72:73]
	v_cmp_gt_u32_e64 s[50:51], 16, v160
	v_addc_co_u32_e64 v164, s[42:43], v164, v164, s[74:75]
	v_cmp_gt_u32_e64 s[72:73], 16, v159
	v_addc_co_u32_e64 v164, s[42:43], v164, v164, s[76:77]
	v_cmp_gt_u32_e64 s[74:75], 16, v158
	v_addc_co_u32_e64 v164, s[42:43], v164, v164, s[50:51]
	v_cmp_gt_u32_e64 s[76:77], 16, v157
	v_addc_co_u32_e64 v164, s[42:43], v164, v164, s[72:73]
	v_cmp_gt_u32_e64 s[50:51], 16, v156
	v_addc_co_u32_e64 v164, s[42:43], v164, v164, s[74:75]
	v_addc_co_u32_e64 v164, s[42:43], v164, v164, s[76:77]
	v_addc_co_u32_e64 v164, s[42:43], v164, v164, s[50:51]
	ds_write_b8 v165, v164 offset:55808
	v_add_u32_e32 v135, 0, v0
	v_lshl_add_u32 v0, v128, 3, 0
	s_waitcnt lgkmcnt(0)
	s_barrier
	ds_read_b64 v[96:97], v0 offset:55808
	ds_read_b128 v[0:3], v193 offset:55808
	ds_read_b128 v[4:7], v193 offset:55824
	ds_read_b128 v[8:11], v193 offset:55840
	ds_read_b128 v[12:15], v193 offset:55856
	s_waitcnt vmcnt(1)
	ds_read_b128 v[16:19], v193 offset:55872
	s_waitcnt vmcnt(0)
	ds_read_b128 v[20:23], v193 offset:55888
	ds_read_b128 v[24:27], v193 offset:55904
	ds_read_b128 v[28:31], v193 offset:55920
	ds_read_b128 v[32:35], v193 offset:55936
	ds_read_b128 v[36:39], v193 offset:55952
	ds_read_b128 v[40:43], v193 offset:55968
	ds_read_b128 v[44:47], v193 offset:55984
	ds_read_b128 v[48:51], v193 offset:56000
	ds_read_b128 v[52:55], v193 offset:56016
	ds_read_b128 v[56:59], v193 offset:56032
	ds_read_b128 v[60:63], v193 offset:56048
	ds_read_b128 v[80:83], v193 offset:56064
	ds_read_b128 v[84:87], v193 offset:56080
	ds_read_b128 v[98:101], v193 offset:56096
	ds_read_b128 v[102:105], v193 offset:56112
	ds_read_b128 v[106:109], v193 offset:56128
	ds_read_b128 v[110:113], v193 offset:56144
	ds_read_b128 v[114:117], v193 offset:56160
	ds_read_b128 v[118:121], v193 offset:56176
	ds_read_b128 v[122:125], v193 offset:56192
	ds_read_b128 v[126:129], v193 offset:56208
	ds_read_b128 v[140:143], v193 offset:56224
	ds_read_b128 v[144:147], v193 offset:56240
	ds_read_b128 v[148:151], v193 offset:56256
	ds_read_b128 v[152:155], v193 offset:56272
	ds_read_b128 v[156:159], v193 offset:56288
	ds_read_b128 v[160:163], v193 offset:56304
	s_waitcnt lgkmcnt(14)
	v_or_b32_e32 v0, v2, v0
	v_or_b32_e32 v1, v3, v1
	v_or_b32_e32 v0, v0, v4
	v_or_b32_e32 v1, v1, v5
	v_or_b32_e32 v0, v0, v6
	v_or_b32_e32 v1, v1, v7
	v_or_b32_e32 v0, v0, v8
	v_or_b32_e32 v1, v1, v9
	v_or_b32_e32 v0, v0, v10
	v_or_b32_e32 v1, v1, v11
	v_or_b32_e32 v0, v0, v12
	v_or_b32_e32 v1, v1, v13
	v_or_b32_e32 v0, v0, v14
	v_or_b32_e32 v1, v1, v15
	v_or_b32_e32 v0, v0, v16
	v_or_b32_e32 v1, v1, v17
	v_or_b32_e32 v0, v0, v18
	v_or_b32_e32 v1, v1, v19
	v_or_b32_e32 v0, v0, v20
	v_or_b32_e32 v1, v1, v21
	v_or_b32_e32 v0, v0, v22
	v_or_b32_e32 v1, v1, v23
	v_or_b32_e32 v0, v0, v24
	v_or_b32_e32 v1, v1, v25
	v_or_b32_e32 v0, v0, v26
	v_or_b32_e32 v1, v1, v27
	v_or_b32_e32 v0, v0, v28
	v_or_b32_e32 v1, v1, v29
	v_or_b32_e32 v0, v0, v30
	v_or_b32_e32 v1, v1, v31
	v_or_b32_e32 v0, v0, v32
	v_or_b32_e32 v1, v1, v33
	v_or_b32_e32 v0, v0, v34
	v_or_b32_e32 v1, v1, v35
	v_or_b32_e32 v0, v0, v36
	v_or_b32_e32 v1, v1, v37
	v_or_b32_e32 v0, v0, v38
	v_or_b32_e32 v1, v1, v39
	v_or_b32_e32 v0, v0, v40
	v_or_b32_e32 v1, v1, v41
	v_or_b32_e32 v0, v0, v42
	v_or_b32_e32 v1, v1, v43
	v_or_b32_e32 v0, v0, v44
	v_or_b32_e32 v1, v1, v45
	v_or_b32_e32 v0, v0, v46
	v_or_b32_e32 v1, v1, v47
	v_or_b32_e32 v0, v0, v48
	v_or_b32_e32 v1, v1, v49
	v_or_b32_e32 v0, v0, v50
	v_or_b32_e32 v1, v1, v51
	v_or_b32_e32 v0, v0, v52
	v_or_b32_e32 v1, v1, v53
	v_or_b32_e32 v0, v0, v54
	v_or_b32_e32 v1, v1, v55
	v_or_b32_e32 v0, v0, v56
	v_or_b32_e32 v1, v1, v57
	v_or_b32_e32 v0, v0, v58
	v_or_b32_e32 v1, v1, v59
	v_or_b32_e32 v0, v0, v60
	v_or_b32_e32 v1, v1, v61
	v_or_b32_e32 v0, v0, v62
	v_or_b32_e32 v1, v1, v63
	v_or_b32_e32 v0, v0, v80
	v_or_b32_e32 v1, v1, v81
	v_or_b32_e32 v0, v0, v82
	v_or_b32_e32 v1, v1, v83
	v_or_b32_e32 v0, v0, v84
	v_or_b32_e32 v1, v1, v85
	v_or_b32_e32 v0, v0, v86
	v_or_b32_e32 v1, v1, v87
	s_waitcnt lgkmcnt(13)
	v_or_b32_e32 v0, v0, v98
	v_or_b32_e32 v1, v1, v99
	v_or_b32_e32 v0, v0, v100
	v_or_b32_e32 v1, v1, v101
	s_waitcnt lgkmcnt(12)
	v_or_b32_e32 v0, v0, v102
	v_or_b32_e32 v1, v1, v103
	v_or_b32_e32 v0, v0, v104
	v_or_b32_e32 v1, v1, v105
	s_waitcnt lgkmcnt(11)
	v_or_b32_e32 v0, v0, v106
	v_or_b32_e32 v1, v1, v107
	v_or_b32_e32 v0, v0, v108
	v_or_b32_e32 v1, v1, v109
	s_waitcnt lgkmcnt(10)
	v_or_b32_e32 v0, v0, v110
	v_or_b32_e32 v1, v1, v111
	v_or_b32_e32 v0, v0, v112
	v_or_b32_e32 v1, v1, v113
	s_waitcnt lgkmcnt(9)
	v_or_b32_e32 v0, v0, v114
	v_or_b32_e32 v1, v1, v115
	v_or_b32_e32 v0, v0, v116
	v_or_b32_e32 v1, v1, v117
	s_waitcnt lgkmcnt(8)
	v_or_b32_e32 v0, v0, v118
	v_or_b32_e32 v1, v1, v119
	v_or_b32_e32 v0, v0, v120
	v_or_b32_e32 v1, v1, v121
	s_waitcnt lgkmcnt(7)
	v_or_b32_e32 v0, v0, v122
	v_or_b32_e32 v1, v1, v123
	v_or_b32_e32 v0, v0, v124
	v_or_b32_e32 v1, v1, v125
	s_waitcnt lgkmcnt(6)
	v_or_b32_e32 v0, v0, v126
	v_or_b32_e32 v1, v1, v127
	v_or_b32_e32 v0, v0, v128
	v_or_b32_e32 v1, v1, v129
	s_waitcnt lgkmcnt(5)
	v_or_b32_e32 v0, v0, v140
	v_or_b32_e32 v1, v1, v141
	v_or_b32_e32 v0, v0, v142
	v_or_b32_e32 v1, v1, v143
	s_waitcnt lgkmcnt(4)
	v_or_b32_e32 v0, v0, v144
	v_or_b32_e32 v1, v1, v145
	v_or_b32_e32 v0, v0, v146
	v_or_b32_e32 v1, v1, v147
	s_waitcnt lgkmcnt(3)
	v_or_b32_e32 v0, v0, v148
	v_or_b32_e32 v1, v1, v149
	v_or_b32_e32 v0, v0, v150
	v_or_b32_e32 v1, v1, v151
	s_waitcnt lgkmcnt(2)
	v_or_b32_e32 v0, v0, v152
	v_or_b32_e32 v1, v1, v153
	s_sub_i32 s0, 64, s45
	v_or_b32_e32 v0, v0, v154
	v_or_b32_e32 v1, v1, v155
	s_lshl_b64 s[0:1], -1, s0
	s_waitcnt lgkmcnt(1)
	v_or_b32_e32 v0, v0, v156
	v_or_b32_e32 v1, v1, v157
	s_add_i32 s39, s39, s47
	s_not_b64 s[0:1], s[0:1]
	v_or_b32_e32 v0, v0, v158
	v_or_b32_e32 v1, v1, v159
	s_cmp_gt_u32 s41, 7
	s_waitcnt lgkmcnt(0)
	v_or_b32_e32 v0, v0, v160
	v_or_b32_e32 v1, v1, v161
	s_cselect_b32 s1, s1, -1
	s_cselect_b32 s0, s0, -1
	v_or_b32_e32 v0, v0, v162
	v_or_b32_e32 v1, v1, v163
	v_and_b32_e32 v0, s0, v0
	v_and_b32_e32 v1, s1, v1
	v_add_u32_e32 v139, s25, v133
	v_cmp_eq_u64_e32 vcc, 0, v[0:1]
	s_lshl_b32 s44, s44, 19
	s_lshl_b32 s41, s40, 6
	s_lshl_b32 s40, s46, 18
	v_mov_b32_e32 v2, v195
	v_add_u32_e32 v137, 0xffffff41, v139
	v_or_b32_e32 v138, 31, v139
	s_cbranch_vccnz .LBB0_801
; DI void task_nsa(const P& p, int layer, int task, bf16_t* sm, int dm) {
;     ...
;     const bf16_t* kg = (const bf16_t*)(p.ws + O_KS) + (size_t)b * S_ * 128 + g * 64;
;     const bf16_t* vg = (const bf16_t*)(p.ws + O_VST) + (size_t)((b * 2 + g) * 64) * S_;
; #pragma unroll
;     for (int dt = 0; dt < 2; ++dt)
; #pragma unroll
;       for (int i = 0; i < 16; ++i) O[dt][i] = 0.f;
;     float m = -1e30f, l = 0.f;
;     kv_gload(R, kg, 128, vg, S_, (__ffsll((long long)todo) - 1) * 64);
	s_lshl_b32 s0, s44, 1
	v_readlane_b32 s2, v253, 40
	v_readlane_b32 s3, v253, 41
	s_add_u32 s0, s2, s0
	v_ashrrev_i32_e32 v4, 3, v2
	s_addc_u32 s1, s3, 0
	s_lshl_b32 s2, s41, 1
	v_ashrrev_i32_e32 v5, 31, v4
	s_add_u32 s0, s0, s2
	v_lshlrev_b64 v[6:7], 13, v[4:5]
	v_ffbl_b32_e32 v5, v1
	s_addc_u32 s1, s1, 0
	s_lshl_b32 s2, s40, 1
	v_readlane_b32 s4, v253, 38
	v_ffbl_b32_e32 v3, v0
	v_add_u32_e64 v5, v5, 32 clamp
	v_readlane_b32 s5, v253, 39
	s_add_u32 s6, s4, s2
	v_min_u32_e32 v5, v5, v3
	s_addc_u32 s7, s5, 0
	v_lshl_add_u32 v4, v5, 6, v4
	v_lshl_add_u64 v[6:7], s[6:7], 0, v[6:7]
	v_lshlrev_b32_e32 v192, 7, v5
	v_lshlrev_b32_e32 v2, 4, v2
	v_ashrrev_i32_e32 v5, 31, v4
	v_lshl_add_u64 v[6:7], v[6:7], 0, v[192:193]
	v_and_b32_e32 v192, 0x70, v2
	v_lshlrev_b64 v[4:5], 8, v[4:5]
	v_lshl_add_u64 v[2:3], v[6:7], 0, v[192:193]
	v_lshl_add_u64 v[4:5], s[0:1], 0, v[4:5]
	v_lshl_add_u64 v[4:5], v[4:5], 0, v[192:193]
	global_load_dwordx4 v[84:87], v[2:3], off
	global_load_dwordx4 v[80:83], v[4:5], off
	v_mov_b32_e32 v140, 0
	v_mov_b32_e32 v88, 0xf149f2ca
	v_mov_b32_e32 v130, 0
	v_mov_b32_e32 v131, v140
	v_mov_b32_e32 v128, 0
	v_mov_b32_e32 v129, v140
	v_mov_b32_e32 v126, 0
	v_mov_b32_e32 v127, v140
	v_mov_b32_e32 v124, 0
	v_mov_b32_e32 v125, v140
	v_mov_b32_e32 v116, 0
	v_mov_b32_e32 v117, v140
	v_mov_b32_e32 v112, 0
	v_mov_b32_e32 v113, v140
	v_mov_b32_e32 v110, 0
	v_mov_b32_e32 v111, v140
	v_mov_b32_e32 v108, 0
	v_mov_b32_e32 v109, v140
	v_mov_b32_e32 v122, 0
	v_mov_b32_e32 v123, v140
	v_mov_b32_e32 v120, 0
	v_mov_b32_e32 v121, v140
	v_mov_b32_e32 v118, 0
	v_mov_b32_e32 v119, v140
	v_mov_b32_e32 v114, 0
	v_mov_b32_e32 v115, v140
	v_mov_b32_e32 v106, 0
	v_mov_b32_e32 v107, v140
	v_mov_b32_e32 v104, 0
	v_mov_b32_e32 v105, v140
	v_mov_b32_e32 v102, 0
	v_mov_b32_e32 v103, v140
	v_mov_b32_e32 v100, 0
	v_mov_b32_e32 v101, v140
	v_mov_b64_e32 v[160:161], 0
	v_mov_b64_e32 v[162:163], 0
	v_mov_b64_e32 v[164:165], 0
	v_mov_b64_e32 v[166:167], 0
	v_mov_b64_e32 v[168:169], 0
	v_mov_b64_e32 v[170:171], 0
	v_mov_b64_e32 v[172:173], 0
	v_mov_b64_e32 v[174:175], 0
	v_mov_b64_e32 v[176:177], 0
	v_mov_b64_e32 v[178:179], 0
	v_mov_b64_e32 v[180:181], 0
	v_mov_b64_e32 v[182:183], 0
	v_mov_b64_e32 v[184:185], 0
	v_mov_b64_e32 v[186:187], 0
	v_mov_b64_e32 v[188:189], 0
	v_mov_b64_e32 v[190:191], 0

; DI int tidx() { int t = threadIdx.x; asm volatile("" : "+v"(t)); return t; }
; DI void task_attnA(const P& p, int layer, int task, bf16_t* sm, int dm) {
;   const int tid = tidx(), lane = tid & 63, wv = tid >> 6, c = wv & 1, qs = wv >> 1;
;   const int lr = lane & 31, lh = lane >> 5;
;   const int qb = 31 - (task >> 4), bh = task & 15, b = bh >> 2, h = bh & 3;
;   float* tab = (float*)((unsigned char*)sm + 71680);
;   bf16x8* qlds = (bf16x8*)((unsigned char*)sm + 72704) + wv * 256 + lane;
;   float* xbuf = (float*)((unsigned char*)sm);
;   __syncthreads();
;   if (tid < 129) tab[tid] = ((const float*)(p.ws + O_TABS))[h * 132 + tid];
;   const int q0 = qb * 128, qmin = q0 + qs * 32, qp = qmin + lr;
;   bf16_t* aq = (bf16_t*)(p.ws + O_AQ);
;   {
;     const bf16_t* qptr = aq + (size_t)(b * S_ + qp) * 512 + h * 128 + c * 64 + lh * 8;
; #pragma unroll
;     for (int ks = 0; ks < 4; ++ks) qlds[ks * 64] = *(const bf16x8*)(qptr + ks * 16);
;   }
;   f32x16 O[4];
; #pragma unroll
;   for (int dt = 0; dt < 4; ++dt)
; #pragma unroll
;     for (int i = 0; i < 16; ++i) O[dt][i] = 0.f;
;   float m = -1e30f, l = 0.f;
;   const bf16_t* kg = (const bf16_t*)(p.ws + O_AK) + (size_t)b * S_ * 512 + h * 128;
;   const bf16_t* vg = (const bf16_t*)(p.ws + O_AVT) + (size_t)((b * 4 + h) * 128) * S_;
;   u32x4 rk0, rk1, rv0, rv1;
;     ...
;   const int kt_hi = 2 * qb + 1;
;   A_GLOAD(0, 0) A_GLOAD(1, 0)
.LBB0_974:
	s_or_b64 exec, exec, s[0:1]
	v_mov_b32_e32 v246, 0xf149f2ca
	v_lshlrev_b32_e32 v244, 2, v195
	v_add_u32_e32 v244, 0x1e000, v244
	s_waitcnt vmcnt(0)
	v_cmp_gt_u32_e64 s[98:99], s101, v247
	s_nop 1
	v_cndmask_b32_e64 v196, v246, v196, s[98:99]
	ds_write_b32 v244, v196
	s_add_i32 s3, s34, -16
	s_lshr_b32 s0, s3, 4
	s_xor_b32 s4, s0, 31
	v_ashrrev_i32_e32 v0, 2, v138
	s_lshl_b32 s5, s4, 7
	v_and_b32_e32 v27, 0xffffffe0, v0
	v_and_b32_e32 v139, 31, v138
	v_add_u32_e32 v28, s5, v27
	s_bfe_u32 s0, s34, 0x20002
	v_or_b32_e32 v0, v28, v139
	v_lshl_add_u32 v0, s0, 12, v0
	s_lshl_b32 s66, s2, 8
	s_lshl_b32 s0, s0, 22
	s_add_u32 s0, s56, s0
	v_ashrrev_i32_e32 v16, 4, v138
	s_addc_u32 s1, s57, 0
	v_ashrrev_i32_e32 v17, 31, v16
	s_add_u32 s0, s0, s66
	v_lshlrev_b64 v[18:19], 10, v[16:17]
	v_lshlrev_b32_e32 v17, 3, v138
	s_addc_u32 s1, s1, 0
	s_lshl_b32 s2, s3, 20
	v_and_b32_e32 v20, 0x78, v17
	s_and_b32 s2, s2, 0xf00000
	v_readlane_b32 s6, v253, 50
	v_lshlrev_b32_e32 v126, 1, v20
	v_ashrrev_i32_e32 v20, 3, v138
	v_readlane_b32 s7, v253, 51
	s_add_u32 s2, s6, s2
	v_ashrrev_i32_e32 v21, 31, v20
	v_ashrrev_i32_e32 v1, 31, v0
	s_addc_u32 s3, s7, 0
	v_lshlrev_b64 v[22:23], 13, v[20:21]
	v_and_b32_e32 v17, 56, v17
	v_ashrrev_i32_e32 v26, 6, v138
	v_lshlrev_b64 v[0:1], 10, v[0:1]
	v_lshl_add_u64 v[22:23], s[2:3], 0, v[22:23]
	v_lshlrev_b32_e32 v128, 1, v17
	v_mov_b32_e32 v129, v193
	v_add_u32_e32 v17, 0x200, v138
	v_and_b32_e32 v140, 1, v26
	v_lshl_add_u64 v[0:1], s[58:59], 0, v[0:1]
	v_lshl_add_u64 v[130:131], v[22:23], 0, v[128:129]
	v_ashrrev_i32_e32 v22, 4, v17
	v_bfe_u32 v137, v138, 5, 1
	v_lshl_add_u64 v[124:125], v[0:1], 0, s[66:67]
	v_lshlrev_b32_e32 v192, 7, v140
	v_ashrrev_i32_e32 v23, 31, v22
	v_lshl_add_u64 v[0:1], v[124:125], 0, v[192:193]
	v_lshlrev_b32_e32 v192, 4, v137
	v_lshl_add_u64 v[18:19], s[0:1], 0, v[18:19]
	v_mov_b32_e32 v127, v193
	v_lshlrev_b64 v[24:25], 10, v[22:23]
	v_lshl_add_u64 v[12:13], v[0:1], 0, v[192:193]
	v_lshl_add_u64 v[18:19], v[18:19], 0, v[126:127]
	v_lshl_add_u64 v[24:25], s[0:1], 0, v[24:25]
	global_load_dwordx4 v[0:3], v[12:13], off
	global_load_dwordx4 v[4:7], v[12:13], off offset:32
	global_load_dwordx4 v[8:11], v[12:13], off offset:64
	s_nop 0
	global_load_dwordx4 v[12:15], v[12:13], off offset:96
	v_lshl_add_u64 v[24:25], v[24:25], 0, v[126:127]
	global_load_dwordx4 v[96:99], v[18:19], off
	global_load_dwordx4 v[104:107], v[24:25], off
	v_ashrrev_i32_e32 v18, 3, v17
	v_ashrrev_i32_e32 v19, 31, v18
	v_lshlrev_b64 v[24:25], 13, v[18:19]
	v_lshl_add_u64 v[24:25], s[2:3], 0, v[24:25]
	v_lshl_add_u64 v[132:133], v[24:25], 0, v[128:129]
	global_load_dwordx4 v[100:103], v[130:131], off
	global_load_dwordx4 v[108:111], v[132:133], off
	v_and_b32_e32 v17, 63, v138
	v_lshlrev_b32_e32 v19, 12, v26
	v_lshlrev_b32_e32 v17, 4, v17
	v_readlane_b32 s3, v255, 5
	v_mov_b32_e32 v48, v193
	v_mov_b32_e32 v49, v193
	s_movk_i32 s2, 0x110
	v_add3_u32 v143, s3, v19, v17
	v_lshl_add_u64 v[134:135], s[0:1], 0, v[126:127]
	s_sub_i32 s0, s5, 59
	v_mov_b32_e32 v50, v193
	v_mul_lo_u32 v129, v16, s2
	v_mul_lo_u32 v141, v20, s89
	v_add_u32_e32 v142, 64, v16
	v_mul_lo_u32 v145, v22, s2
	v_mul_lo_u32 v146, v18, s89
	v_add_u32_e32 v147, 64, v22
	v_or_b32_e32 v148, 31, v28
	v_add_u32_e32 v149, 0xffffff41, v28
	s_lshl_b32 s6, s4, 1
	s_mov_b32 s66, 0
	v_add3_u32 v127, s0, v27, v139
	v_mov_b32_e32 v51, v193
	v_mov_b32_e32 v52, v193
	v_mov_b32_e32 v53, v193
	v_mov_b32_e32 v54, v193
	v_mov_b32_e32 v55, v193
	v_mov_b32_e32 v56, v193
	s_waitcnt vmcnt(7)
	ds_write_b128 v143, v[0:3]
	s_waitcnt vmcnt(6)
	ds_write_b128 v143, v[4:7] offset:1024
	s_waitcnt vmcnt(5)
	ds_write_b128 v143, v[8:11] offset:2048
	s_waitcnt vmcnt(4)
	ds_write_b128 v143, v[12:15] offset:3072
	v_mov_b32_e32 v57, v193
	v_mov_b32_e32 v58, v193
	v_mov_b32_e32 v59, v193
	v_mov_b32_e32 v60, v193
	v_mov_b32_e32 v61, v193
	v_mov_b32_e32 v62, v193
	v_mov_b32_e32 v63, v193
	v_mov_b64_e32 v[32:33], v[48:49]
	v_mov_b64_e32 v[16:17], v[48:49]
	v_mov_b64_e32 v[0:1], v[48:49]
	v_lshlrev_b32_e32 v144, 6, v140
	s_add_i32 s7, s6, 2
	v_mov_b32_e32 v154, 0xf149f2ca
	v_mov_b32_e32 v151, 0
	v_mov_b64_e32 v[34:35], v[50:51]
	v_mov_b64_e32 v[36:37], v[52:53]
	v_mov_b64_e32 v[38:39], v[54:55]
	v_mov_b64_e32 v[40:41], v[56:57]
	v_mov_b64_e32 v[42:43], v[58:59]
	v_mov_b64_e32 v[44:45], v[60:61]
	v_mov_b64_e32 v[46:47], v[62:63]
	v_mov_b64_e32 v[18:19], v[50:51]
	v_mov_b64_e32 v[20:21], v[52:53]
	v_mov_b64_e32 v[22:23], v[54:55]
	v_mov_b64_e32 v[24:25], v[56:57]
	v_mov_b64_e32 v[26:27], v[58:59]
	v_mov_b64_e32 v[28:29], v[60:61]
	v_mov_b64_e32 v[30:31], v[62:63]
	v_mov_b64_e32 v[2:3], v[50:51]
	v_mov_b64_e32 v[4:5], v[52:53]
	v_mov_b64_e32 v[6:7], v[54:55]
	v_mov_b64_e32 v[8:9], v[56:57]
	v_mov_b64_e32 v[10:11], v[58:59]
	v_mov_b64_e32 v[12:13], v[60:61]
	v_mov_b64_e32 v[14:15], v[62:63]
	s_mov_b32 s8, s66
	s_branch .LBB0_978
.Lisland_LBB0_1210:
	s_branch .LBB0_1210

; #define MFMA32(a, b, c) __builtin_amdgcn_mfma_f32_32x32x16_bf16((a), (b), (c), 0, 0, 0)
; DI unsigned pack2(float a, float b) { f32x2_t v = {a, b}; bf16x2_t r = __builtin_convertvector(v, bf16x2_t); return __builtin_bit_cast(unsigned, r); }
; DI float ex2(float x) { return __builtin_amdgcn_exp2f(x); }
; template <int NDT, int MODE, bool ALLON>
; DI void attn_tile(const bf16_t* Kl, int kst, const bf16_t* Vl, const bf16x8 (&q)[4], f32x16 (&O)[NDT], float& m, float& l,
;                   int kbase, int qp, int win, float cbias, const float* tab, bool lane_on) {
;     ...
; #pragma unroll
;     for (int st = 0; st < 2; ++st)
; #pragma unroll
;       for (int i = 0; i < 16; ++i) {
;         const float pe = s[st][i] > -5e29f ? ex2(s[st][i] - mn) : 0.f;
;         psum += pe;
;         s[st][i] = pe;
;       }
;   }
;   l = l * alpha + psum;
;   if (__ballot(alpha != 1.f)) {
; #pragma unroll
;     for (int dt = 0; dt < NDT; ++dt)
; #pragma unroll
;       for (int i = 0; i < 16; ++i) O[dt][i] *= alpha;
;   }
; #pragma unroll
;   for (int st = 0; st < 2; ++st)
; #pragma unroll
;     for (int sk = 0; sk < 2; ++sk) {
;       u32x4 pu;
;       pu[0] = pack2(s[st][8 * sk + 0], s[st][8 * sk + 1]);
;       pu[1] = pack2(s[st][8 * sk + 2], s[st][8 * sk + 3]);
;       pu[2] = pack2(s[st][8 * sk + 4], s[st][8 * sk + 5]);
;       pu[3] = pack2(s[st][8 * sk + 6], s[st][8 * sk + 7]);
;       const bf16x8 pf = __builtin_bit_cast(bf16x8, pu);
; #pragma unroll
;       for (int dt = 0; dt < NDT; ++dt) {
;         const bf16_t* vp = Vl + (dt * 32 + lr) * 72 + st * 32 + sk * 16 + 4 * lh;
;         const uint2 v0 = *(const uint2*)(vp);
;         const uint2 v1 = *(const uint2*)(vp + 8);
;         u32x4 vu; vu[0] = v0.x; vu[1] = v0.y; vu[2] = v1.x; vu[3] = v1.y;
;         O[dt] = MFMA32(__builtin_bit_cast(bf16x8, vu), pf, O[dt]);
.Lisland_LBB0_250:
	s_branch .LBB0_250
.LBB0_975:
	v_sub_f32_e32 v74, v120, v150
	v_exp_f32_e32 v74, v74
	v_sub_f32_e32 v75, v116, v150
	v_exp_f32_e32 v75, v75
	v_cmp_lt_f32_e32 vcc, s11, v120
	s_nop 1
	v_cndmask_b32_e32 v76, 0, v74, vcc
	v_cmp_lt_f32_e32 vcc, s11, v116
	v_add_f32_e32 v74, 0, v76
	s_nop 0
	v_cndmask_b32_e32 v78, 0, v75, vcc
	v_sub_f32_e32 v75, v119, v150
	v_exp_f32_e32 v75, v75
	v_cmp_lt_f32_e32 vcc, s11, v119
	v_add_f32_e32 v74, v78, v74
	s_nop 0
	v_cndmask_b32_e32 v90, 0, v75, vcc
	v_sub_f32_e32 v75, v114, v150
	v_exp_f32_e32 v75, v75
	v_cmp_lt_f32_e32 vcc, s11, v114
	v_add_f32_e32 v74, v90, v74
	s_nop 0
	v_cndmask_b32_e32 v93, 0, v75, vcc
	v_sub_f32_e32 v75, v118, v150
	v_exp_f32_e32 v75, v75
	v_cmp_lt_f32_e32 vcc, s11, v118
	v_add_f32_e32 v74, v93, v74
	v_cvt_pk_bf16_f32 v118, v76, v78
	v_cndmask_b32_e32 v95, 0, v75, vcc
	v_sub_f32_e32 v75, v113, v150
	v_exp_f32_e32 v75, v75
	v_cmp_lt_f32_e32 vcc, s11, v113
	v_add_f32_e32 v74, v95, v74
	v_cvt_pk_bf16_f32 v119, v90, v93
	v_cndmask_b32_e32 v113, 0, v75, vcc
	v_sub_f32_e32 v75, v117, v150
	v_exp_f32_e32 v75, v75
	v_cmp_lt_f32_e32 vcc, s11, v117
	v_add_f32_e32 v74, v113, v74
	v_cvt_pk_bf16_f32 v120, v95, v113
	v_cndmask_b32_e32 v116, 0, v75, vcc
	v_sub_f32_e32 v75, v112, v150
	v_exp_f32_e32 v75, v75
	v_cmp_lt_f32_e32 vcc, s11, v112
	v_add_f32_e32 v74, v116, v74
	s_nop 0
	v_cndmask_b32_e32 v117, 0, v75, vcc
	v_add_f32_e32 v75, v117, v74
	v_sub_f32_e32 v74, v115, v150
	v_exp_f32_e32 v74, v74
	v_cmp_lt_f32_e32 vcc, s11, v115
	s_nop 1
	v_cndmask_b32_e32 v74, 0, v74, vcc
	v_add_f32_e32 v77, v74, v75
	v_sub_f32_e32 v75, v85, v150
	v_exp_f32_e32 v75, v75
	v_cmp_lt_f32_e32 vcc, s11, v85
	v_sub_f32_e32 v85, v87, v150
	v_exp_f32_e32 v85, v85
	v_cndmask_b32_e32 v75, 0, v75, vcc
	v_add_f32_e32 v79, v75, v77
	v_sub_f32_e32 v77, v88, v150
	v_exp_f32_e32 v77, v77
	v_cmp_lt_f32_e32 vcc, s11, v88
	s_nop 1
	v_cndmask_b32_e32 v77, 0, v77, vcc
	v_cmp_lt_f32_e32 vcc, s11, v83
	v_sub_f32_e32 v83, v83, v150
	v_exp_f32_e32 v83, v83
	v_add_f32_e32 v79, v77, v79
	v_cndmask_b32_e32 v83, 0, v83, vcc
	v_cmp_lt_f32_e32 vcc, s11, v87
	v_add_f32_e32 v79, v83, v79
	s_nop 0
	v_cndmask_b32_e32 v85, 0, v85, vcc
	v_cmp_lt_f32_e32 vcc, s11, v81
	v_sub_f32_e32 v81, v81, v150
	v_exp_f32_e32 v81, v81
	v_add_f32_e32 v79, v85, v79
	v_cndmask_b32_e32 v94, 0, v81, vcc
	v_sub_f32_e32 v81, v86, v150
	v_exp_f32_e32 v81, v81
	v_cmp_lt_f32_e32 vcc, s11, v86
	v_add_f32_e32 v79, v94, v79
	s_nop 0
	v_cndmask_b32_e32 v112, 0, v81, vcc
	v_cmp_lt_f32_e32 vcc, s11, v80
	v_sub_f32_e32 v80, v80, v150
	v_exp_f32_e32 v80, v80
	v_add_f32_e32 v79, v112, v79
	v_cndmask_b32_e32 v114, 0, v80, vcc
	v_add_f32_e32 v80, v114, v79
	v_sub_f32_e32 v79, v84, v150
	v_exp_f32_e32 v79, v79
	v_cmp_lt_f32_e32 vcc, s11, v84
	s_nop 1
	v_cndmask_b32_e32 v79, 0, v79, vcc
	v_add_f32_e32 v81, v79, v80
	v_sub_f32_e32 v80, v82, v150
	v_exp_f32_e32 v80, v80
	v_cmp_lt_f32_e32 vcc, s11, v82
	s_nop 1
	v_cndmask_b32_e32 v80, 0, v80, vcc
	v_add_f32_e32 v82, v80, v81
	v_sub_f32_e32 v81, v89, v150
	v_exp_f32_e32 v81, v81
	v_cmp_lt_f32_e32 vcc, s11, v89
	v_mul_u32_u24_e32 v89, 0x48, v152
	v_lshlrev_b32_e32 v76, 1, v89
	v_cndmask_b32_e32 v81, 0, v81, vcc
	v_cmp_lt_f32_e32 vcc, s11, v65
	v_sub_f32_e32 v65, v65, v150
	v_exp_f32_e32 v65, v65
	v_add_f32_e32 v84, v81, v82
	v_cvt_pk_bf16_f32 v80, v79, v80
	v_cndmask_b32_e32 v82, 0, v65, vcc
	v_cmp_lt_f32_e32 vcc, s11, v67
	v_sub_f32_e32 v67, v67, v150
	v_exp_f32_e32 v67, v67
	v_add_f32_e32 v65, v82, v84
	v_cvt_pk_bf16_f32 v81, v81, v82
	v_cndmask_b32_e32 v84, 0, v67, vcc
	v_cmp_lt_f32_e32 vcc, s11, v66
	v_sub_f32_e32 v66, v66, v150
	v_exp_f32_e32 v66, v66
	v_add_f32_e32 v65, v84, v65
	v_cndmask_b32_e32 v86, 0, v66, vcc
	v_sub_f32_e32 v66, v69, v150
	v_exp_f32_e32 v66, v66
	v_cmp_lt_f32_e32 vcc, s11, v69
	v_add_f32_e32 v65, v86, v65
	v_sub_f32_e32 v69, v72, v150
	v_cndmask_b32_e32 v87, 0, v66, vcc
	v_sub_f32_e32 v66, v68, v150
	v_exp_f32_e32 v66, v66
	v_cmp_lt_f32_e32 vcc, s11, v68
	v_add_f32_e32 v65, v87, v65
	v_exp_f32_e32 v69, v69
	v_cndmask_b32_e32 v88, 0, v66, vcc
	v_add_f32_e32 v66, v88, v65
	v_sub_f32_e32 v65, v71, v150
	v_exp_f32_e32 v65, v65
	v_cmp_lt_f32_e32 vcc, s11, v71
	v_sub_f32_e32 v71, v91, v150
	v_exp_f32_e32 v71, v71
	v_cndmask_b32_e32 v65, 0, v65, vcc
	v_add_f32_e32 v67, v65, v66
	v_sub_f32_e32 v66, v70, v150
	v_exp_f32_e32 v66, v66
	v_cmp_lt_f32_e32 vcc, s11, v70
	v_sub_f32_e32 v70, v92, v150
	v_exp_f32_e32 v70, v70
	v_cndmask_b32_e32 v66, 0, v66, vcc
	v_add_f32_e32 v68, v66, v67
	v_sub_f32_e32 v67, v73, v150
	v_exp_f32_e32 v67, v67
	v_cmp_lt_f32_e32 vcc, s11, v73
	v_sub_f32_e32 v73, v121, v150
	v_exp_f32_e32 v73, v73
	v_cndmask_b32_e32 v67, 0, v67, vcc
	v_cmp_lt_f32_e32 vcc, s11, v72
	v_sub_f32_e32 v72, v122, v150
	v_exp_f32_e32 v72, v72
	v_add_f32_e32 v68, v67, v68
	v_cndmask_b32_e32 v69, 0, v69, vcc
	v_cmp_lt_f32_e32 vcc, s11, v92
	v_add_f32_e32 v68, v69, v68
	v_cvt_pk_bf16_f32 v82, v84, v86
	v_cndmask_b32_e32 v70, 0, v70, vcc
	v_cmp_lt_f32_e32 vcc, s11, v91
	v_add_f32_e32 v68, v70, v68
	s_nop 0
	v_cndmask_b32_e32 v71, 0, v71, vcc
	v_cmp_lt_f32_e32 vcc, s11, v122
	v_add_f32_e32 v68, v71, v68
	s_nop 0
	v_cndmask_b32_e32 v72, 0, v72, vcc
	v_cmp_lt_f32_e32 vcc, s11, v121
	v_add_f32_e32 v68, v72, v68
	v_cvt_pk_bf16_f32 v121, v116, v117
	v_cndmask_b32_e32 v73, 0, v73, vcc
	v_add_f32_e32 v68, v73, v68
	v_fmac_f32_e32 v68, v151, v64
	v_lshlrev_b32_e32 v64, 3, v153
	v_add3_u32 v76, s9, v64, v76
	v_add_u32_e32 v64, 0x4000, v76
	ds_read2_b64 v[90:93], v64 offset0:128 offset1:130
	ds_read2_b64 v[152:155], v64 offset0:132 offset1:134
	v_add_u32_e32 v78, 0x5000, v76
	s_waitcnt lgkmcnt(1)
; #define MFMA32(a, b, c) __builtin_amdgcn_mfma_f32_32x32x16_bf16((a), (b), (c), 0, 0, 0)
; DI unsigned pack2(float a, float b) { f32x2_t v = {a, b}; bf16x2_t r = __builtin_convertvector(v, bf16x2_t); return __builtin_bit_cast(unsigned, r); }
; template <int NDT, int MODE, bool ALLON>
; DI void attn_tile(const bf16_t* Kl, int kst, const bf16_t* Vl, const bf16x8 (&q)[4], f32x16 (&O)[NDT], float& m, float& l,
;                   int kbase, int qp, int win, float cbias, const float* tab, bool lane_on) {
;     ...
; #pragma unroll
;   for (int st = 0; st < 2; ++st)
; #pragma unroll
;     for (int sk = 0; sk < 2; ++sk) {
;       u32x4 pu;
;       pu[0] = pack2(s[st][8 * sk + 0], s[st][8 * sk + 1]);
;       pu[1] = pack2(s[st][8 * sk + 2], s[st][8 * sk + 3]);
;       pu[2] = pack2(s[st][8 * sk + 4], s[st][8 * sk + 5]);
;       pu[3] = pack2(s[st][8 * sk + 6], s[st][8 * sk + 7]);
;       const bf16x8 pf = __builtin_bit_cast(bf16x8, pu);
; #pragma unroll
;       for (int dt = 0; dt < NDT; ++dt) {
;         const bf16_t* vp = Vl + (dt * 32 + lr) * 72 + st * 32 + sk * 16 + 4 * lh;
;         const uint2 v0 = *(const uint2*)(vp);
;         const uint2 v1 = *(const uint2*)(vp + 8);
;         u32x4 vu; vu[0] = v0.x; vu[1] = v0.y; vu[2] = v1.x; vu[3] = v1.y;
;         O[dt] = MFMA32(__builtin_bit_cast(bf16x8, vu), pf, O[dt]);
;       }
;     }
	v_mfma_f32_32x32x16_bf16 v[48:63], v[90:93], v[118:121], v[48:63]
	ds_read2_b64 v[90:93], v78 offset0:192 offset1:194
	v_add_u32_e32 v89, 0x6800, v76
	v_add_u32_e32 v76, 0x7800, v76
	s_waitcnt lgkmcnt(0)
	v_mfma_f32_32x32x16_bf16 v[32:47], v[90:93], v[118:121], v[32:47]
	ds_read2_b64 v[90:93], v89 offset1:2
	s_waitcnt lgkmcnt(0)
	v_mfma_f32_32x32x16_bf16 v[16:31], v[90:93], v[118:121], v[16:31]
	ds_read2_b64 v[90:93], v76 offset0:64 offset1:66
	s_waitcnt lgkmcnt(0)
	v_mfma_f32_32x32x16_bf16 v[0:15], v[90:93], v[118:121], v[0:15]
	v_cvt_pk_bf16_f32 v90, v74, v75
	v_cvt_pk_bf16_f32 v91, v77, v83
	v_cvt_pk_bf16_f32 v92, v85, v94
	v_cvt_pk_bf16_f32 v93, v112, v114
	v_cvt_pk_bf16_f32 v83, v87, v88
	ds_read2_b64 v[84:87], v64 offset0:136 offset1:138
	ds_read2_b64 v[112:115], v78 offset0:196 offset1:198
	v_mfma_f32_32x32x16_bf16 v[48:63], v[152:155], v[90:93], v[48:63]
	s_waitcnt lgkmcnt(1)
	v_mfma_f32_32x32x16_bf16 v[48:63], v[84:87], v[80:83], v[48:63]
	ds_read2_b64 v[84:87], v78 offset0:200 offset1:202
	s_waitcnt lgkmcnt(1)
	v_mfma_f32_32x32x16_bf16 v[32:47], v[112:115], v[90:93], v[32:47]
	ds_read2_b64 v[112:115], v89 offset0:4 offset1:6
	s_waitcnt lgkmcnt(1)
	v_mfma_f32_32x32x16_bf16 v[32:47], v[84:87], v[80:83], v[32:47]
	ds_read2_b64 v[84:87], v89 offset0:8 offset1:10
	s_waitcnt lgkmcnt(1)
	v_mfma_f32_32x32x16_bf16 v[16:31], v[112:115], v[90:93], v[16:31]
	ds_read2_b64 v[112:115], v76 offset0:68 offset1:70
	s_waitcnt lgkmcnt(1)
	v_mfma_f32_32x32x16_bf16 v[16:31], v[84:87], v[80:83], v[16:31]
	ds_read2_b64 v[84:87], v76 offset0:72 offset1:74
	s_waitcnt lgkmcnt(1)
	v_mfma_f32_32x32x16_bf16 v[0:15], v[112:115], v[90:93], v[0:15]
	s_waitcnt lgkmcnt(0)
	v_mfma_f32_32x32x16_bf16 v[0:15], v[84:87], v[80:83], v[0:15]
	v_cvt_pk_bf16_f32 v80, v65, v66
	v_cvt_pk_bf16_f32 v81, v67, v69
	ds_read2_b64 v[64:67], v64 offset0:140 offset1:142
	v_cvt_pk_bf16_f32 v82, v70, v71
	v_cvt_pk_bf16_f32 v83, v72, v73
	s_waitcnt lgkmcnt(0)
	s_nop 0
	v_mfma_f32_32x32x16_bf16 v[48:63], v[64:67], v[80:83], v[48:63]
	ds_read2_b64 v[64:67], v78 offset0:204 offset1:206
	s_waitcnt lgkmcnt(0)
	v_mfma_f32_32x32x16_bf16 v[32:47], v[64:67], v[80:83], v[32:47]
	ds_read2_b64 v[64:67], v89 offset0:12 offset1:14
	s_waitcnt lgkmcnt(0)
	v_mfma_f32_32x32x16_bf16 v[16:31], v[64:67], v[80:83], v[16:31]
	ds_read2_b64 v[64:67], v76 offset0:76 offset1:78
	s_waitcnt lgkmcnt(0)
	v_mfma_f32_32x32x16_bf16 v[0:15], v[64:67], v[80:83], v[0:15]
